# kloop-a-stage-reschedule-also-down-sout-cgu
# baseline (speedup 1.0000x reference)
; #define PG8_STAGE(bufoff, gbase, hoff, imm) do { _Pragma("unroll") for (int _i = 0; _i < 2; ++_i) { \
;         asm volatile("s_mov_b32 m0, %0\n\ts_nop 0\n\tglobal_load_lds_dwordx4 %1, %2" \
;             :: "s"(lds0 + (unsigned)((bufoff) + _i * 8192)), "v"(voff0), "s"((const char*)(gbase) + (size_t)(hoff) + (size_t)(_i * 8192)) : "memory"); } } while (0)
; #define PG8_WAIT_V(n) asm volatile("s_waitcnt vmcnt(" #n ")" ::: "memory")
; #define PG8_BAR __builtin_amdgcn_s_barrier()
; template <class Epi>
; __device__ __forceinline__ void gemm_phase(LAS unsigned char* lds, const Gemm g, const StaticOrder& S, const Epi& E) {
;     ...
;     const int wid = __builtin_amdgcn_readfirstlane(tid >> 6), lane = tid & 63, wr = wid >> 2, wc = wid & 3, fr = lane & 15, fq = lane >> 4;
;     const int K = g.K, nt = K / BK;
;     const unsigned voff0 = (unsigned)(tid * 16);
;     const unsigned hA = (unsigned)(g.lda * 256), hB = (unsigned)(K * 256);
;     constexpr int KS = 16384;
;     const size_t tstepA = (size_t)BM * g.lda * 2, tstepB = (size_t)BM * K * 2;
;     const unsigned lds0 = (unsigned)__builtin_amdgcn_readfirstlane((int)((unsigned)(size_t)lds + (unsigned)wid * 1024u));
;     const int aoff = lds_byte(wr * 64 + fr, fq * 8), boff = lds_byte(wc * 32 + fr, fq * 8);
;     ...
;     PG8_WAIT_V(4); PG8_BAR;
;     PG8_STAGE(PG8_SB(1, 0), cB + KS, 0, 0); PG8_STAGE(PG8_SA(1, 0), cA + KS, 0, 0); PG8_STAGE(PG8_SB(1, 1), cB + KS, hB, 0);
;     PG8_WAIT_V(6); PG8_BAR;
.LBB0_497:
	s_add_u32 s10, s56, 0x1a630000
	s_addc_u32 s11, s57, 0
	s_add_u32 s52, s56, 0x12630000
	s_addc_u32 s53, s57, 0
	s_add_u32 s54, s56, 0x28630000
	s_addc_u32 s55, s57, 0
	s_add_u32 s56, s56, 0x29130000
	v_and_b32_e32 v169, 15, v0
	v_lshrrev_b32_e32 v1, 1, v0
	v_and_b32_e32 v171, 48, v0
	v_lshlrev_b32_e32 v0, 2, v0
	s_addc_u32 s57, s57, 0
	s_and_b32 s48, s8, 3
	s_lshl_b32 s9, s1, 13
	v_lshl_or_b32 v2, v169, 6, v171
	v_and_b32_e32 v0, 32, v0
	s_lshl_b32 s37, s1, 6
	v_bitop3_b32 v3, v2, s9, v0 bitop3:0xde
	s_lshl_b32 s9, s48, 12
	s_add_i32 s38, s24, 0x18000
	s_add_u32 s40, s80, 0x4000
	s_addc_u32 s41, s81, 0
	s_add_i32 s39, s24, 0x1a000
	s_waitcnt vmcnt(4)
	s_barrier
	s_mov_b32 m0, s38
	s_nop 0
	global_load_lds_dwordx4 v168, s[40:41]
	s_add_u32 s40, s80, 0x6000
	s_addc_u32 s41, s81, 0
	s_mov_b32 m0, s39
	s_nop 0
	global_load_lds_dwordx4 v168, s[40:41]
	s_add_i32 s40, s24, 0x8000
	s_add_u32 s42, s78, 0x4000
	s_addc_u32 s43, s79, 0
	s_add_i32 s41, s24, 0xa000
	s_mov_b32 m0, s40
	s_nop 0
	global_load_lds_dwordx4 v168, s[42:43]
	s_add_u32 s42, s78, 0x6000
	s_addc_u32 s43, s79, 0
	s_mov_b32 m0, s41
	s_nop 0
	global_load_lds_dwordx4 v168, s[42:43]
	s_add_i32 s42, s24, 0x1c000
	s_add_u32 s50, s80, 0x84000
	s_addc_u32 s51, s81, 0
	s_add_i32 s43, s24, 0x1e000
	s_mov_b32 m0, s42
	s_nop 0
	global_load_lds_dwordx4 v168, s[50:51]
	s_add_u32 s50, s80, 0x86000
	s_addc_u32 s51, s81, 0
	s_cmp_lt_i32 s8, 4
	v_readlane_b32 s49, v255, 38
	s_cselect_b64 s[58:59], -1, 0
	s_add_i32 s12, s49, s12
	v_bitop3_b32 v0, v2, s9, v0 bitop3:0xde
	s_ashr_i32 s9, s8, 31
	s_add_i32 s86, s12, 0x2000
	s_add_i32 s87, s24, 0xc000
	s_lshl_b32 s12, s1, 11
	s_cmp_gt_i32 s1, 0
	s_cselect_b64 s[60:61], -1, 0
	s_cmp_gt_i32 s1, -2
	s_cselect_b64 s[64:65], -1, 0
	s_add_i32 s12, s49, s12
	s_cmpk_lt_u32 s0, 0x100
	s_mov_b32 m0, s43
	s_nop 0
	global_load_lds_dwordx4 v168, s[50:51]
	s_cselect_b64 s[50:51], -1, 0
	s_bfe_u32 s89, s0, 0x10006
	s_lshl_b32 s0, s1, 3
	s_and_b32 s0, s0, 8
	v_cmp_gt_u32_e32 vcc, 2, v169
	s_or_b32 s0, s0, s89
	v_writelane_b32 v255, s50, 48
	s_and_b64 s[66:67], s[50:51], vcc
	s_lshl_b32 s92, s0, 10
	s_add_i32 s96, s24, 0xe000
	s_add_u32 s0, s78, 0x84000
	s_addc_u32 s1, s79, 0
	s_mov_b32 m0, s87
	s_nop 0
	global_load_lds_dwordx4 v168, s[0:1]
	s_add_u32 s0, s78, 0x86000
	s_addc_u32 s1, s79, 0
	s_mov_b32 m0, s96
	s_nop 0
	global_load_lds_dwordx4 v168, s[0:1]
	s_lshl_b64 s[0:1], s[8:9], 13
	v_and_b32_e32 v1, 24, v1
	s_add_u32 s0, s4, s0
	v_writelane_b32 v255, s51, 49
	s_addc_u32 s1, s5, s1
	v_lshl_or_b32 v173, s48, 5, v1
	s_cmp_eq_u32 s8, 3
	v_lshlrev_b32_e32 v1, 2, v173
	v_readlane_b32 s8, v255, 39
	v_readlane_b32 s9, v255, 40
	v_readlane_b32 s48, v255, 41
	v_readlane_b32 s49, v255, 42
	s_waitcnt vmcnt(8)
	v_lshlrev_b32_e32 v2, 10, v169
	v_add_u32_e32 v174, s12, v1
	v_add_u32_e32 v180, s8, v1
	v_add_u32_e32 v181, s9, v1
	v_add_u32_e32 v182, s48, v1
	v_add_u32_e32 v183, s49, v1
	v_or_b32_e32 v1, 16, v1
	s_waitcnt vmcnt(0)
	v_add_u32_e32 v4, v174, v2
	v_or_b32_e32 v184, 0xfffff800, v2
	v_add_u32_e32 v185, s8, v1
	v_add_u32_e32 v186, s9, v1
	v_add_u32_e32 v187, s48, v1
	v_add_u32_e32 v200, s49, v1
	v_add_u32_e32 v1, s12, v1
	s_cselect_b32 s97, s7, s1
	s_cselect_b32 s12, s6, s0
	v_readlane_b32 s6, v255, 23
	v_or_b32_e32 v170, s37, v169
	v_and_b32_e32 v172, 0x1f0, v168
	s_mov_b32 s88, 0
	v_cmp_lt_u32_e64 s[4:5], 13, v169
	v_add_u32_e32 v175, 0xffffc800, v4
	v_add_u32_e32 v176, 0xffffc810, v4
	v_add_u32_e32 v177, 0xffffd800, v4
	v_add_u32_e32 v178, 0xffffd810, v4
	v_add_u32_e32 v179, -14, v169
	v_add_u32_e32 v201, v1, v184
	v_add_u32_e32 v202, 0, v0
	v_add_u32_e32 v203, 0, v3
	v_readlane_b32 s0, v255, 21
	s_mov_b32 s50, s6
	s_barrier
	v_readlane_b32 s7, v255, 24
	s_branch .LBB0_499

; #define PG8_STAGE(bufoff, gbase, hoff, imm) do { _Pragma("unroll") for (int _i = 0; _i < 2; ++_i) { \
;         asm volatile("s_mov_b32 m0, %0\n\ts_nop 0\n\tglobal_load_lds_dwordx4 %1, %2" \
;             :: "s"(lds0 + (unsigned)((bufoff) + _i * 8192)), "v"(voff0), "s"((const char*)(gbase) + (size_t)(hoff) + (size_t)(_i * 8192)) : "memory"); } } while (0)
; #define PG8_LDA(dst, b, h) do { _Pragma("unroll") for (int m = 0; m < 4; ++m) _Pragma("unroll") for (int k = 0; k < 2; ++k) dst[m][k] = *(const LAS bf16x8*)(lds + PG8_SA(b, h) + aoff + m * 2048 + k * 1024); } while (0)
; #define PG8_LDB(dst, b, h) do { _Pragma("unroll") for (int n = 0; n < 2; ++n) _Pragma("unroll") for (int k = 0; k < 2; ++k) dst[n][k] = *(const LAS bf16x8*)(lds + PG8_SB(b, h) + boff + n * 2048 + k * 1024); } while (0)
; #define PG8_MMA(ai, bj, At, Bt) do { __builtin_amdgcn_s_setprio(1); _Pragma("unroll") for (int m = 0; m < 4; ++m) _Pragma("unroll") for (int n = 0; n < 2; ++n) _Pragma("unroll") for (int k = 0; k < 2; ++k) \
;         acc[ai][bj][m][n] = __builtin_amdgcn_mfma_f32_16x16x32_bf16(Bt[n][k], At[m][k], acc[ai][bj][m][n], 0, 0, 0); __builtin_amdgcn_s_setprio(0); } while (0)
; #define PG8_WAIT_L(n) asm volatile("s_waitcnt lgkmcnt(" #n ")" ::: "memory")
; #define PG8_BAR __builtin_amdgcn_s_barrier()
; #define PG8_SCHED __builtin_amdgcn_sched_barrier(0)
; template <class Epi>
; __device__ __forceinline__ void gemm_phase(LAS unsigned char* lds, const Gemm g, const StaticOrder& S, const Epi& E) {
;     ...
;             const char* aT = cA + (size_t)t * KS;
;             const char* a2 = last ? nA : aT + 2 * KS; const char* b2 = last ? nB : cB + (size_t)(t + 2) * KS;
;             PG8_LDB(B0, 0, 0); PG8_SCHED; PG8_LDA(At, 0, 0); PG8_STAGE(PG8_SA(1, 1), aT + KS, hA, 0);
;             PG8_WAIT_L(8); PG8_BAR; PG8_WAIT_L(0); PG8_MMA(0, 0, At, B0); PG8_BAR; PG8_SCHED;
;             PG8_LDB(B1, 0, 1); PG8_STAGE(PG8_SB(0, 0), b2, 0, 0);
;             PG8_BAR; PG8_WAIT_L(0); PG8_MMA(0, 1, At, B1); PG8_BAR;
;             PG8_LDA(At, 0, 1); PG8_STAGE(PG8_SA(0, 0), a2, 0, 0);
;             PG8_BAR; PG8_WAIT_L(0); PG8_MMA(1, 0, At, B0); PG8_BAR; PG8_SCHED;
.LBB0_506:
	v_add_u32_e32 v140, 0x10000, v202
	ds_read_b128 v[128:131], v140
	ds_read_b128 v[132:135], v140 offset:1024
	ds_read_b128 v[136:139], v140 offset:2048
	ds_read_b128 v[140:143], v140 offset:3072
	s_add_u32 s80, s78, 0x8000
	s_addc_u32 s81, s79, 0
	s_and_b64 s[82:83], s[84:85], exec
	s_cselect_b32 s83, s51, s81
	s_cselect_b32 s82, s71, s80
	ds_read_b128 v[144:147], v203
	ds_read_b128 v[148:151], v203 offset:1024
	ds_read_b128 v[152:155], v203 offset:2048
	ds_read_b128 v[156:159], v203 offset:3072
	ds_read_b128 v[160:163], v203 offset:4096
	ds_read_b128 v[164:167], v203 offset:5120
	ds_read_b128 v[204:207], v203 offset:6144
	ds_read_b128 v[208:211], v203 offset:7168
	s_add_u32 s48, s78, 0x84000
	s_addc_u32 s49, s79, 0
	s_add_u32 s48, s78, 0x86000
	s_addc_u32 s49, s79, 0
	s_waitcnt lgkmcnt(8)
	s_waitcnt vmcnt(10)
	s_barrier
	s_waitcnt lgkmcnt(0)
	s_waitcnt lgkmcnt(7)
	v_mfma_f32_16x16x32_bf16 v[96:99], v[128:131], v[144:147], v[96:99]
	v_mfma_f32_16x16x32_bf16 v[44:47], v[136:139], v[144:147], v[44:47]
	s_waitcnt lgkmcnt(5)
	v_mfma_f32_16x16x32_bf16 v[92:95], v[128:131], v[152:155], v[92:95]
	v_mfma_f32_16x16x32_bf16 v[40:43], v[136:139], v[152:155], v[40:43]
	s_waitcnt lgkmcnt(3)
	v_mfma_f32_16x16x32_bf16 v[84:87], v[128:131], v[160:163], v[84:87]
	v_mfma_f32_16x16x32_bf16 v[36:39], v[136:139], v[160:163], v[36:39]
	s_waitcnt lgkmcnt(1)
	v_mfma_f32_16x16x32_bf16 v[124:127], v[128:131], v[204:207], v[124:127]
	v_mfma_f32_16x16x32_bf16 v[120:123], v[136:139], v[204:207], v[120:123]
	v_mfma_f32_16x16x32_bf16 v[96:99], v[132:135], v[148:151], v[96:99]
	v_mfma_f32_16x16x32_bf16 v[44:47], v[140:143], v[148:151], v[44:47]
	v_mfma_f32_16x16x32_bf16 v[92:95], v[132:135], v[156:159], v[92:95]
	v_mfma_f32_16x16x32_bf16 v[40:43], v[140:143], v[156:159], v[40:43]
	v_mfma_f32_16x16x32_bf16 v[84:87], v[132:135], v[164:167], v[84:87]
	v_mfma_f32_16x16x32_bf16 v[36:39], v[140:143], v[164:167], v[36:39]
	s_waitcnt lgkmcnt(0)
	v_mfma_f32_16x16x32_bf16 v[124:127], v[132:135], v[208:211], v[124:127]
	v_mfma_f32_16x16x32_bf16 v[120:123], v[140:143], v[208:211], v[120:123]
	s_barrier
	v_add_u32_e32 v188, 0x14000, v202
	ds_read_b128 v[212:215], v188
	ds_read_b128 v[236:239], v188 offset:1024
	ds_read_b128 v[240:243], v188 offset:2048
	ds_read_b128 v[244:247], v188 offset:3072
	s_and_b64 s[48:49], s[84:85], exec
	s_cselect_b32 s78, s62, s9
	s_cselect_b32 s79, s69, s63
	s_mov_b32 m0, s25
	s_nop 0
	global_load_lds_dwordx4 v168, s[78:79]
	s_add_u32 s48, s78, 0x2000
	s_addc_u32 s49, s79, 0
	s_mov_b32 m0, s26
	s_nop 0
	global_load_lds_dwordx4 v168, s[48:49]
	s_waitcnt vmcnt(10)
	s_barrier
	s_waitcnt lgkmcnt(0)
	s_waitcnt lgkmcnt(3)
	v_mfma_f32_16x16x32_bf16 v[80:83], v[212:215], v[144:147], v[80:83]
	s_waitcnt lgkmcnt(1)
	v_mfma_f32_16x16x32_bf16 v[32:35], v[240:243], v[144:147], v[32:35]
	v_mfma_f32_16x16x32_bf16 v[76:79], v[212:215], v[152:155], v[76:79]
	v_mfma_f32_16x16x32_bf16 v[28:31], v[240:243], v[152:155], v[28:31]
	v_mfma_f32_16x16x32_bf16 v[72:75], v[212:215], v[160:163], v[72:75]
	v_mfma_f32_16x16x32_bf16 v[24:27], v[240:243], v[160:163], v[24:27]
	v_mfma_f32_16x16x32_bf16 v[116:119], v[212:215], v[204:207], v[116:119]
	v_mfma_f32_16x16x32_bf16 v[112:115], v[240:243], v[204:207], v[112:115]
	v_mfma_f32_16x16x32_bf16 v[80:83], v[236:239], v[148:151], v[80:83]
	s_waitcnt lgkmcnt(0)
	v_mfma_f32_16x16x32_bf16 v[32:35], v[244:247], v[148:151], v[32:35]
	v_mfma_f32_16x16x32_bf16 v[76:79], v[236:239], v[156:159], v[76:79]
	v_mfma_f32_16x16x32_bf16 v[28:31], v[244:247], v[156:159], v[28:31]
	v_mfma_f32_16x16x32_bf16 v[72:75], v[236:239], v[164:167], v[72:75]
	v_mfma_f32_16x16x32_bf16 v[24:27], v[244:247], v[164:167], v[24:27]
	v_mfma_f32_16x16x32_bf16 v[116:119], v[236:239], v[208:211], v[116:119]
	v_mfma_f32_16x16x32_bf16 v[112:115], v[244:247], v[208:211], v[112:115]
	s_barrier
	ds_read_b128 v[144:147], v203 offset:16384
	ds_read_b128 v[148:151], v203 offset:17408
	ds_read_b128 v[152:155], v203 offset:18432
	ds_read_b128 v[156:159], v203 offset:19456
	ds_read_b128 v[160:163], v203 offset:20480
	ds_read_b128 v[164:167], v203 offset:21504
	ds_read_b128 v[204:207], v203 offset:22528
	ds_read_b128 v[208:211], v203 offset:23552
	s_mov_b32 m0, s24
	s_nop 0
	global_load_lds_dwordx4 v168, s[82:83]
	s_add_u32 s48, s82, 0x2000
	s_addc_u32 s49, s83, 0
	s_mov_b32 m0, s27
	s_nop 0
	global_load_lds_dwordx4 v168, s[48:49]
	s_barrier
	s_waitcnt lgkmcnt(0)
	s_waitcnt lgkmcnt(7)
	v_mfma_f32_16x16x32_bf16 v[68:71], v[128:131], v[144:147], v[68:71]
	v_mfma_f32_16x16x32_bf16 v[20:23], v[136:139], v[144:147], v[20:23]
	s_waitcnt lgkmcnt(5)
	v_mfma_f32_16x16x32_bf16 v[64:67], v[128:131], v[152:155], v[64:67]
	v_mfma_f32_16x16x32_bf16 v[16:19], v[136:139], v[152:155], v[16:19]
	s_waitcnt lgkmcnt(3)
	v_mfma_f32_16x16x32_bf16 v[60:63], v[128:131], v[160:163], v[60:63]
	v_mfma_f32_16x16x32_bf16 v[12:15], v[136:139], v[160:163], v[12:15]
	s_waitcnt lgkmcnt(1)
	v_mfma_f32_16x16x32_bf16 v[108:111], v[128:131], v[204:207], v[108:111]
	v_mfma_f32_16x16x32_bf16 v[104:107], v[136:139], v[204:207], v[104:107]
	v_mfma_f32_16x16x32_bf16 v[68:71], v[132:135], v[148:151], v[68:71]
	v_mfma_f32_16x16x32_bf16 v[20:23], v[140:143], v[148:151], v[20:23]
	v_mfma_f32_16x16x32_bf16 v[64:67], v[132:135], v[156:159], v[64:67]
	v_mfma_f32_16x16x32_bf16 v[16:19], v[140:143], v[156:159], v[16:19]
	v_mfma_f32_16x16x32_bf16 v[60:63], v[132:135], v[164:167], v[60:63]
	v_mfma_f32_16x16x32_bf16 v[12:15], v[140:143], v[164:167], v[12:15]
	s_waitcnt lgkmcnt(0)
	v_mfma_f32_16x16x32_bf16 v[108:111], v[132:135], v[208:211], v[108:111]
	v_mfma_f32_16x16x32_bf16 v[104:107], v[140:143], v[208:211], v[104:107]
	s_barrier
; #define PG8_STAGE(bufoff, gbase, hoff, imm) do { _Pragma("unroll") for (int _i = 0; _i < 2; ++_i) { \
;         asm volatile("s_mov_b32 m0, %0\n\ts_nop 0\n\tglobal_load_lds_dwordx4 %1, %2" \
;             :: "s"(lds0 + (unsigned)((bufoff) + _i * 8192)), "v"(voff0), "s"((const char*)(gbase) + (size_t)(hoff) + (size_t)(_i * 8192)) : "memory"); } } while (0)
; #define PG8_LDA(dst, b, h) do { _Pragma("unroll") for (int m = 0; m < 4; ++m) _Pragma("unroll") for (int k = 0; k < 2; ++k) dst[m][k] = *(const LAS bf16x8*)(lds + PG8_SA(b, h) + aoff + m * 2048 + k * 1024); } while (0)
; #define PG8_LDB(dst, b, h) do { _Pragma("unroll") for (int n = 0; n < 2; ++n) _Pragma("unroll") for (int k = 0; k < 2; ++k) dst[n][k] = *(const LAS bf16x8*)(lds + PG8_SB(b, h) + boff + n * 2048 + k * 1024); } while (0)
; #define PG8_MMA(ai, bj, At, Bt) do { __builtin_amdgcn_s_setprio(1); _Pragma("unroll") for (int m = 0; m < 4; ++m) _Pragma("unroll") for (int n = 0; n < 2; ++n) _Pragma("unroll") for (int k = 0; k < 2; ++k) \
;         acc[ai][bj][m][n] = __builtin_amdgcn_mfma_f32_16x16x32_bf16(Bt[n][k], At[m][k], acc[ai][bj][m][n], 0, 0, 0); __builtin_amdgcn_s_setprio(0); } while (0)
; #define PG8_WAIT_V(n) asm volatile("s_waitcnt vmcnt(" #n ")" ::: "memory")
; #define PG8_WAIT_L(n) asm volatile("s_waitcnt lgkmcnt(" #n ")" ::: "memory")
; #define PG8_BAR __builtin_amdgcn_s_barrier()
; #define PG8_SCHED __builtin_amdgcn_sched_barrier(0)
; template <class Epi>
; __device__ __forceinline__ void gemm_phase(LAS unsigned char* lds, const Gemm g, const StaticOrder& S, const Epi& E) {
;     ...
;             PG8_STAGE(PG8_SB(0, 1), b2, hB, 0);
;             PG8_WAIT_V(6); PG8_BAR; PG8_MMA(1, 1, At, B1); PG8_BAR;
;             PG8_LDB(B0, 1, 0); PG8_SCHED; PG8_LDA(At, 1, 0); PG8_STAGE(PG8_SA(0, 1), a2, hA, 0);
;             PG8_WAIT_L(8); PG8_BAR; PG8_WAIT_L(0); PG8_MMA(0, 0, At, B0); PG8_BAR; PG8_SCHED;
;             PG8_LDB(B1, 1, 1); PG8_STAGE(PG8_SB(1, 0), b2 + KS, 0, 0);
	s_add_u32 s48, s78, 0x80000
	s_addc_u32 s49, s79, 0
	s_mov_b32 m0, s28
	s_nop 0
	global_load_lds_dwordx4 v168, s[48:49]
	s_add_u32 s48, s78, 0x82000
	s_addc_u32 s49, s79, 0
	s_mov_b32 m0, s29
	s_nop 0
	global_load_lds_dwordx4 v168, s[48:49]
	s_add_u32 s48, s82, 0x80000
	s_addc_u32 s49, s83, 0
	s_mov_b32 m0, s30
	s_nop 0
	global_load_lds_dwordx4 v168, s[48:49]
	s_add_u32 s48, s82, 0x82000
	s_addc_u32 s49, s83, 0
	s_mov_b32 m0, s34
	s_nop 0
	global_load_lds_dwordx4 v168, s[48:49]
	s_waitcnt vmcnt(12)
	s_barrier
	v_mfma_f32_16x16x32_bf16 v[56:59], v[212:215], v[144:147], v[56:59]
	v_mfma_f32_16x16x32_bf16 v[8:11], v[240:243], v[144:147], v[8:11]
	v_mfma_f32_16x16x32_bf16 v[52:55], v[212:215], v[152:155], v[52:55]
	v_mfma_f32_16x16x32_bf16 v[4:7], v[240:243], v[152:155], v[4:7]
	v_mfma_f32_16x16x32_bf16 v[48:51], v[212:215], v[160:163], v[48:51]
	v_mfma_f32_16x16x32_bf16 v[0:3], v[240:243], v[160:163], v[0:3]
	v_mfma_f32_16x16x32_bf16 v[100:103], v[212:215], v[204:207], v[100:103]
	v_mfma_f32_16x16x32_bf16 v[88:91], v[240:243], v[204:207], v[88:91]
	v_mfma_f32_16x16x32_bf16 v[56:59], v[236:239], v[148:151], v[56:59]
	v_mfma_f32_16x16x32_bf16 v[8:11], v[244:247], v[148:151], v[8:11]
	v_mfma_f32_16x16x32_bf16 v[52:55], v[236:239], v[156:159], v[52:55]
	v_mfma_f32_16x16x32_bf16 v[4:7], v[244:247], v[156:159], v[4:7]
	v_mfma_f32_16x16x32_bf16 v[48:51], v[236:239], v[164:167], v[48:51]
	v_mfma_f32_16x16x32_bf16 v[0:3], v[244:247], v[164:167], v[0:3]
	v_mfma_f32_16x16x32_bf16 v[100:103], v[236:239], v[208:211], v[100:103]
	v_mfma_f32_16x16x32_bf16 v[88:91], v[244:247], v[208:211], v[88:91]
	v_add_u32_e32 v140, 0x18000, v202
	s_barrier
	ds_read_b128 v[128:131], v140
	ds_read_b128 v[132:135], v140 offset:1024
	ds_read_b128 v[136:139], v140 offset:2048
	ds_read_b128 v[140:143], v140 offset:3072
	ds_read_b128 v[144:147], v203 offset:32768
	ds_read_b128 v[148:151], v203 offset:33792
	ds_read_b128 v[152:155], v203 offset:34816
	ds_read_b128 v[156:159], v203 offset:35840
	ds_read_b128 v[160:163], v203 offset:36864
	ds_read_b128 v[164:167], v203 offset:37888
	ds_read_b128 v[204:207], v203 offset:38912
	ds_read_b128 v[208:211], v203 offset:39936
	s_waitcnt lgkmcnt(8)
	s_waitcnt vmcnt(10)
	s_barrier
	s_waitcnt lgkmcnt(0)
	s_waitcnt lgkmcnt(7)
	v_mfma_f32_16x16x32_bf16 v[96:99], v[128:131], v[144:147], v[96:99]
	v_mfma_f32_16x16x32_bf16 v[44:47], v[136:139], v[144:147], v[44:47]
	s_waitcnt lgkmcnt(5)
	v_mfma_f32_16x16x32_bf16 v[92:95], v[128:131], v[152:155], v[92:95]
	v_mfma_f32_16x16x32_bf16 v[40:43], v[136:139], v[152:155], v[40:43]
	s_waitcnt lgkmcnt(3)
	v_mfma_f32_16x16x32_bf16 v[84:87], v[128:131], v[160:163], v[84:87]
	v_mfma_f32_16x16x32_bf16 v[36:39], v[136:139], v[160:163], v[36:39]
	s_waitcnt lgkmcnt(1)
	v_mfma_f32_16x16x32_bf16 v[124:127], v[128:131], v[204:207], v[124:127]
	v_mfma_f32_16x16x32_bf16 v[120:123], v[136:139], v[204:207], v[120:123]
	v_mfma_f32_16x16x32_bf16 v[96:99], v[132:135], v[148:151], v[96:99]
	v_mfma_f32_16x16x32_bf16 v[44:47], v[140:143], v[148:151], v[44:47]
	v_mfma_f32_16x16x32_bf16 v[92:95], v[132:135], v[156:159], v[92:95]
	v_mfma_f32_16x16x32_bf16 v[40:43], v[140:143], v[156:159], v[40:43]
	v_mfma_f32_16x16x32_bf16 v[84:87], v[132:135], v[164:167], v[84:87]
	v_mfma_f32_16x16x32_bf16 v[36:39], v[140:143], v[164:167], v[36:39]
	s_waitcnt lgkmcnt(0)
	v_mfma_f32_16x16x32_bf16 v[124:127], v[132:135], v[208:211], v[124:127]
	v_mfma_f32_16x16x32_bf16 v[120:123], v[140:143], v[208:211], v[120:123]
	s_barrier
	v_add_u32_e32 v188, 0x1c000, v202
	ds_read_b128 v[212:215], v188
	ds_read_b128 v[236:239], v188 offset:1024
	ds_read_b128 v[240:243], v188 offset:2048
	ds_read_b128 v[244:247], v188 offset:3072
	s_add_u32 s48, s78, 0x4000
	s_addc_u32 s49, s79, 0
	s_mov_b32 m0, s38
	s_nop 0
	global_load_lds_dwordx4 v168, s[48:49]
	s_add_u32 s48, s78, 0x6000
	s_addc_u32 s49, s79, 0
	s_mov_b32 m0, s39
	s_nop 0
	global_load_lds_dwordx4 v168, s[48:49]
	s_waitcnt vmcnt(10)
	s_barrier
; #define PG8_STAGE(bufoff, gbase, hoff, imm) do { _Pragma("unroll") for (int _i = 0; _i < 2; ++_i) { \
;         asm volatile("s_mov_b32 m0, %0\n\ts_nop 0\n\tglobal_load_lds_dwordx4 %1, %2" \
;             :: "s"(lds0 + (unsigned)((bufoff) + _i * 8192)), "v"(voff0), "s"((const char*)(gbase) + (size_t)(hoff) + (size_t)(_i * 8192)) : "memory"); } } while (0)
; #define PG8_LDA(dst, b, h) do { _Pragma("unroll") for (int m = 0; m < 4; ++m) _Pragma("unroll") for (int k = 0; k < 2; ++k) dst[m][k] = *(const LAS bf16x8*)(lds + PG8_SA(b, h) + aoff + m * 2048 + k * 1024); } while (0)
; #define PG8_MMA(ai, bj, At, Bt) do { __builtin_amdgcn_s_setprio(1); _Pragma("unroll") for (int m = 0; m < 4; ++m) _Pragma("unroll") for (int n = 0; n < 2; ++n) _Pragma("unroll") for (int k = 0; k < 2; ++k) \
;         acc[ai][bj][m][n] = __builtin_amdgcn_mfma_f32_16x16x32_bf16(Bt[n][k], At[m][k], acc[ai][bj][m][n], 0, 0, 0); __builtin_amdgcn_s_setprio(0); } while (0)
; #define PG8_WAIT_V(n) asm volatile("s_waitcnt vmcnt(" #n ")" ::: "memory")
; #define PG8_WAIT_L(n) asm volatile("s_waitcnt lgkmcnt(" #n ")" ::: "memory")
; #define PG8_BAR __builtin_amdgcn_s_barrier()
; #define PG8_SCHED __builtin_amdgcn_sched_barrier(0)
; template <class Epi>
; __device__ __forceinline__ void gemm_phase(LAS unsigned char* lds, const Gemm g, const StaticOrder& S, const Epi& E) {
;     ...
;             PG8_BAR; PG8_WAIT_L(0); PG8_MMA(0, 1, At, B1); PG8_BAR;
;             PG8_LDA(At, 1, 1); PG8_STAGE(PG8_SA(1, 0), a2 + KS, 0, 0);
;             PG8_BAR; PG8_WAIT_L(0); PG8_MMA(1, 0, At, B0); PG8_BAR; PG8_SCHED;
;             PG8_STAGE(PG8_SB(1, 1), b2 + KS, hB, 0);
;             PG8_WAIT_V(6); PG8_BAR; PG8_MMA(1, 1, At, B1); PG8_BAR;
;         }
	s_waitcnt lgkmcnt(0)
	s_waitcnt lgkmcnt(3)
	v_mfma_f32_16x16x32_bf16 v[80:83], v[212:215], v[144:147], v[80:83]
	s_waitcnt lgkmcnt(1)
	v_mfma_f32_16x16x32_bf16 v[32:35], v[240:243], v[144:147], v[32:35]
	v_mfma_f32_16x16x32_bf16 v[76:79], v[212:215], v[152:155], v[76:79]
	v_mfma_f32_16x16x32_bf16 v[28:31], v[240:243], v[152:155], v[28:31]
	v_mfma_f32_16x16x32_bf16 v[72:75], v[212:215], v[160:163], v[72:75]
	v_mfma_f32_16x16x32_bf16 v[24:27], v[240:243], v[160:163], v[24:27]
	v_mfma_f32_16x16x32_bf16 v[116:119], v[212:215], v[204:207], v[116:119]
	v_mfma_f32_16x16x32_bf16 v[112:115], v[240:243], v[204:207], v[112:115]
	v_mfma_f32_16x16x32_bf16 v[80:83], v[236:239], v[148:151], v[80:83]
	s_waitcnt lgkmcnt(0)
	v_mfma_f32_16x16x32_bf16 v[32:35], v[244:247], v[148:151], v[32:35]
	v_mfma_f32_16x16x32_bf16 v[76:79], v[236:239], v[156:159], v[76:79]
	v_mfma_f32_16x16x32_bf16 v[28:31], v[244:247], v[156:159], v[28:31]
	v_mfma_f32_16x16x32_bf16 v[72:75], v[236:239], v[164:167], v[72:75]
	v_mfma_f32_16x16x32_bf16 v[24:27], v[244:247], v[164:167], v[24:27]
	v_mfma_f32_16x16x32_bf16 v[116:119], v[236:239], v[208:211], v[116:119]
	v_mfma_f32_16x16x32_bf16 v[112:115], v[244:247], v[208:211], v[112:115]
	s_barrier
	ds_read_b128 v[144:147], v203 offset:49152
	ds_read_b128 v[148:151], v203 offset:50176
	ds_read_b128 v[152:155], v203 offset:51200
	ds_read_b128 v[156:159], v203 offset:52224
	ds_read_b128 v[160:163], v203 offset:53248
	ds_read_b128 v[164:167], v203 offset:54272
	ds_read_b128 v[204:207], v203 offset:55296
	ds_read_b128 v[208:211], v203 offset:56320
	s_add_u32 s48, s82, 0x4000
	s_addc_u32 s49, s83, 0
	s_mov_b32 m0, s40
	s_nop 0
	global_load_lds_dwordx4 v168, s[48:49]
	s_add_u32 s48, s82, 0x6000
	s_addc_u32 s49, s83, 0
	s_mov_b32 m0, s41
	s_nop 0
	global_load_lds_dwordx4 v168, s[48:49]
	s_barrier
	s_waitcnt lgkmcnt(0)
	s_waitcnt lgkmcnt(7)
	v_mfma_f32_16x16x32_bf16 v[68:71], v[128:131], v[144:147], v[68:71]
	v_mfma_f32_16x16x32_bf16 v[20:23], v[136:139], v[144:147], v[20:23]
	s_waitcnt lgkmcnt(5)
	v_mfma_f32_16x16x32_bf16 v[64:67], v[128:131], v[152:155], v[64:67]
	v_mfma_f32_16x16x32_bf16 v[16:19], v[136:139], v[152:155], v[16:19]
	s_waitcnt lgkmcnt(3)
	v_mfma_f32_16x16x32_bf16 v[60:63], v[128:131], v[160:163], v[60:63]
	v_mfma_f32_16x16x32_bf16 v[12:15], v[136:139], v[160:163], v[12:15]
	s_waitcnt lgkmcnt(1)
	v_mfma_f32_16x16x32_bf16 v[108:111], v[128:131], v[204:207], v[108:111]
	v_mfma_f32_16x16x32_bf16 v[104:107], v[136:139], v[204:207], v[104:107]
	v_mfma_f32_16x16x32_bf16 v[68:71], v[132:135], v[148:151], v[68:71]
	v_mfma_f32_16x16x32_bf16 v[20:23], v[140:143], v[148:151], v[20:23]
	v_mfma_f32_16x16x32_bf16 v[64:67], v[132:135], v[156:159], v[64:67]
	v_mfma_f32_16x16x32_bf16 v[16:19], v[140:143], v[156:159], v[16:19]
	v_mfma_f32_16x16x32_bf16 v[60:63], v[132:135], v[164:167], v[60:63]
	v_mfma_f32_16x16x32_bf16 v[12:15], v[140:143], v[164:167], v[12:15]
	s_waitcnt lgkmcnt(0)
	v_mfma_f32_16x16x32_bf16 v[108:111], v[132:135], v[208:211], v[108:111]
	v_mfma_f32_16x16x32_bf16 v[104:107], v[140:143], v[208:211], v[104:107]
	s_barrier
	s_add_u32 s48, s78, 0x84000
	s_addc_u32 s49, s79, 0
	s_mov_b32 m0, s42
	s_nop 0
	global_load_lds_dwordx4 v168, s[48:49]
	s_add_u32 s48, s78, 0x86000
	s_addc_u32 s49, s79, 0
	s_mov_b32 m0, s43
	s_nop 0
	global_load_lds_dwordx4 v168, s[48:49]
	s_add_u32 s48, s82, 0x84000
	s_addc_u32 s49, s83, 0
	s_mov_b32 m0, s87
	s_nop 0
	global_load_lds_dwordx4 v168, s[48:49]
	s_add_u32 s48, s82, 0x86000
	s_addc_u32 s49, s83, 0
	s_mov_b32 m0, s96
	s_nop 0
	global_load_lds_dwordx4 v168, s[48:49]
	s_waitcnt vmcnt(12)
	s_barrier
	v_mfma_f32_16x16x32_bf16 v[56:59], v[212:215], v[144:147], v[56:59]
	v_mfma_f32_16x16x32_bf16 v[8:11], v[240:243], v[144:147], v[8:11]
	v_mfma_f32_16x16x32_bf16 v[52:55], v[212:215], v[152:155], v[52:55]
	v_mfma_f32_16x16x32_bf16 v[4:7], v[240:243], v[152:155], v[4:7]
	v_mfma_f32_16x16x32_bf16 v[48:51], v[212:215], v[160:163], v[48:51]
	v_mfma_f32_16x16x32_bf16 v[0:3], v[240:243], v[160:163], v[0:3]
	v_mfma_f32_16x16x32_bf16 v[100:103], v[212:215], v[204:207], v[100:103]
	v_mfma_f32_16x16x32_bf16 v[88:91], v[240:243], v[204:207], v[88:91]
	v_mfma_f32_16x16x32_bf16 v[56:59], v[236:239], v[148:151], v[56:59]
	v_mfma_f32_16x16x32_bf16 v[8:11], v[244:247], v[148:151], v[8:11]
	v_mfma_f32_16x16x32_bf16 v[52:55], v[236:239], v[156:159], v[52:55]
	v_mfma_f32_16x16x32_bf16 v[4:7], v[244:247], v[156:159], v[4:7]
	v_mfma_f32_16x16x32_bf16 v[48:51], v[236:239], v[164:167], v[48:51]
	v_mfma_f32_16x16x32_bf16 v[0:3], v[244:247], v[164:167], v[0:3]
	v_mfma_f32_16x16x32_bf16 v[100:103], v[236:239], v[208:211], v[100:103]
	v_mfma_f32_16x16x32_bf16 v[88:91], v[244:247], v[208:211], v[88:91]
	s_add_i32 s0, s0, 2
	s_add_u32 s9, s9, 0x8000
	s_addc_u32 s63, s63, 0
	s_cmp_gt_u32 s0, 29
	s_mov_b64 s[78:79], s[80:81]
	s_barrier
	s_cbranch_scc1 .LBB0_509

; #define PG8_STAGE(bufoff, gbase, hoff, imm) do { _Pragma("unroll") for (int _i = 0; _i < 2; ++_i) { \
;         asm volatile("s_mov_b32 m0, %0\n\ts_nop 0\n\tglobal_load_lds_dwordx4 %1, %2" \
;             :: "s"(lds0 + (unsigned)((bufoff) + _i * 8192)), "v"(voff0), "s"((const char*)(gbase) + (size_t)(hoff) + (size_t)(_i * 8192)) : "memory"); } } while (0)
; #define PG8_WAIT_V(n) asm volatile("s_waitcnt vmcnt(" #n ")" ::: "memory")
; #define PG8_BAR __builtin_amdgcn_s_barrier()
; template <class Epi>
; __device__ __forceinline__ void gemm_phase(LAS unsigned char* lds, const Gemm g, const StaticOrder& S, const Epi& E) {
;     ...
;     const char* cA = (const char*)g.A + (size_t)cur.pm * tstepA + (size_t)(cur.pn >> g.gshift) * g.gstride; const char* cB = (const char*)g.Bt + (size_t)cur.pn * tstepB;
;     PG8_STAGE(PG8_SB(0, 0), cB, 0, 0); PG8_STAGE(PG8_SA(0, 0), cA, 0, 0); PG8_STAGE(PG8_SB(0, 1), cB, hB, 0); PG8_STAGE(PG8_SA(0, 1), cA, hA, 0);
;     if (wr == 1) PG8_BAR;
;     PG8_WAIT_V(4); PG8_BAR;
;     PG8_STAGE(PG8_SB(1, 0), cB + KS, 0, 0); PG8_STAGE(PG8_SA(1, 0), cA + KS, 0, 0); PG8_STAGE(PG8_SB(1, 1), cB + KS, hB, 0);
;     PG8_WAIT_V(6); PG8_BAR;
.LBB0_602:
	s_add_u32 s8, s4, 0x29c30000
	s_addc_u32 s9, s5, 0
	s_cmp_eq_u32 s13, 0
	s_cselect_b64 s[10:11], -1, 0
	s_and_b64 s[10:11], s[2:3], s[10:11]
	s_add_u32 s37, s4, 0x31c34000
	s_addc_u32 s38, s5, 0
	s_and_b64 s[10:11], s[10:11], exec
	s_cselect_b32 s11, s38, s9
	s_cselect_b32 s10, s37, s8
	s_add_u32 s37, s4, 0xa61c000
	v_lshrrev_b32_e32 v2, 1, v0
	s_addc_u32 s38, s5, 0
	v_and_b32_e32 v2, 24, v2
	s_lshl_b32 s0, s0, 5
	v_and_b32_e32 v1, 15, v0
	v_lshlrev_b32_e32 v3, 1, v2
	v_lshlrev_b32_e32 v0, 2, v0
	s_and_b32 s4, s0, 0x60
	v_lshl_or_b32 v233, s1, 6, v1
	v_lshl_or_b32 v1, v1, 6, v3
	s_lshl_b32 s1, s1, 13
	v_and_b32_e32 v0, 32, v0
	s_lshl_b32 s0, s4, 7
	s_add_i32 s39, s22, 0x18000
	v_bitop3_b32 v3, v1, s1, v0 bitop3:0xde
	v_bitop3_b32 v0, v1, s0, v0 bitop3:0xde
	s_add_u32 s0, s62, 0x4000
	s_addc_u32 s1, s63, 0
	s_add_i32 s40, s22, 0x1a000
	s_waitcnt vmcnt(4)
	s_barrier
	s_mov_b32 m0, s39
	s_nop 0
	global_load_lds_dwordx4 v188, s[0:1]
	s_add_u32 s0, s62, 0x6000
	s_addc_u32 s1, s63, 0
	s_add_i32 s41, s22, 0x8000
	s_mov_b32 m0, s40
	s_nop 0
	global_load_lds_dwordx4 v188, s[0:1]
	s_add_u32 s0, s60, 0x4000
	s_addc_u32 s1, s61, 0
	s_add_i32 s42, s22, 0xa000
	s_mov_b32 m0, s41
	s_nop 0
	global_load_lds_dwordx4 v188, s[0:1]
	s_add_u32 s0, s60, 0x6000
	s_addc_u32 s1, s61, 0
	s_add_i32 s43, s22, 0x1c000
	s_mov_b32 m0, s42
	s_nop 0
	global_load_lds_dwordx4 v188, s[0:1]
	s_add_u32 s0, s62, 0x84000
	s_addc_u32 s1, s63, 0
	s_add_i32 s66, s22, 0x1e000
	s_mov_b32 m0, s43
	s_nop 0
	global_load_lds_dwordx4 v188, s[0:1]
	s_add_u32 s0, s62, 0x86000
	s_addc_u32 s1, s63, 0
	s_mov_b32 m0, s66
	s_nop 0
	global_load_lds_dwordx4 v188, s[0:1]
	s_add_u32 s0, s60, 0x84000
	s_addc_u32 s1, s61, 0
	s_add_i32 s34, s22, 0xc000
	s_mov_b32 m0, s34
	s_nop 0
	global_load_lds_dwordx4 v188, s[0:1]
	s_add_u32 s0, s60, 0x86000
	s_addc_u32 s1, s61, 0
	s_add_i32 s34, s22, 0xe000
	s_mov_b32 m0, s34
	s_nop 0
	global_load_lds_dwordx4 v188, s[0:1]
	s_waitcnt vmcnt(8)
	v_readlane_b32 s0, v255, 15
	s_mov_b32 s34, 0
	s_add_i32 s67, s22, 0xc000
	s_add_i32 s68, s22, 0xe000
	v_or_b32_e32 v234, s4, v2
	v_add_u32_e32 v236, 0, v0
	v_add_u32_e32 v237, 0, v3
	v_readlane_b32 s51, v255, 14
	s_mov_b32 s50, s0
	s_barrier
	v_readlane_b32 s1, v255, 16

; #define PG8_STAGE(bufoff, gbase, hoff, imm) do { _Pragma("unroll") for (int _i = 0; _i < 2; ++_i) { \
;         asm volatile("s_mov_b32 m0, %0\n\ts_nop 0\n\tglobal_load_lds_dwordx4 %1, %2" \
;             :: "s"(lds0 + (unsigned)((bufoff) + _i * 8192)), "v"(voff0), "s"((const char*)(gbase) + (size_t)(hoff) + (size_t)(_i * 8192)) : "memory"); } } while (0)
; #define PG8_LDA(dst, b, h) do { _Pragma("unroll") for (int m = 0; m < 4; ++m) _Pragma("unroll") for (int k = 0; k < 2; ++k) dst[m][k] = *(const LAS bf16x8*)(lds + PG8_SA(b, h) + aoff + m * 2048 + k * 1024); } while (0)
; #define PG8_LDB(dst, b, h) do { _Pragma("unroll") for (int n = 0; n < 2; ++n) _Pragma("unroll") for (int k = 0; k < 2; ++k) dst[n][k] = *(const LAS bf16x8*)(lds + PG8_SB(b, h) + boff + n * 2048 + k * 1024); } while (0)
; #define PG8_MMA(ai, bj, At, Bt) do { __builtin_amdgcn_s_setprio(1); _Pragma("unroll") for (int m = 0; m < 4; ++m) _Pragma("unroll") for (int n = 0; n < 2; ++n) _Pragma("unroll") for (int k = 0; k < 2; ++k) \
;         acc[ai][bj][m][n] = __builtin_amdgcn_mfma_f32_16x16x32_bf16(Bt[n][k], At[m][k], acc[ai][bj][m][n], 0, 0, 0); __builtin_amdgcn_s_setprio(0); } while (0)
; #define PG8_WAIT_L(n) asm volatile("s_waitcnt lgkmcnt(" #n ")" ::: "memory")
; #define PG8_BAR __builtin_amdgcn_s_barrier()
; #define PG8_SCHED __builtin_amdgcn_sched_barrier(0)
; template <class Epi>
; __device__ __forceinline__ void gemm_phase(LAS unsigned char* lds, const Gemm g, const StaticOrder& S, const Epi& E) {
;     ...
;             const char* aT = cA + (size_t)t * KS;
;             const char* a2 = last ? nA : aT + 2 * KS; const char* b2 = last ? nB : cB + (size_t)(t + 2) * KS;
;             PG8_LDB(B0, 0, 0); PG8_SCHED; PG8_LDA(At, 0, 0); PG8_STAGE(PG8_SA(1, 1), aT + KS, hA, 0);
;             PG8_WAIT_L(8); PG8_BAR; PG8_WAIT_L(0); PG8_MMA(0, 0, At, B0); PG8_BAR; PG8_SCHED;
;             PG8_LDB(B1, 0, 1); PG8_STAGE(PG8_SB(0, 0), b2, 0, 0);
;             PG8_BAR; PG8_WAIT_L(0); PG8_MMA(0, 1, At, B1); PG8_BAR;
;             PG8_LDA(At, 0, 1); PG8_STAGE(PG8_SA(0, 0), a2, 0, 0);
;             PG8_BAR; PG8_WAIT_L(0); PG8_MMA(1, 0, At, B0); PG8_BAR; PG8_SCHED;
.LBB0_610:
	s_add_u32 s62, s60, 0x8000
	v_add_u32_e32 v132, 0x10000, v236
	s_addc_u32 s63, s61, 0
	ds_read_b128 v[120:123], v132
	ds_read_b128 v[124:127], v132 offset:1024
	ds_read_b128 v[128:131], v132 offset:2048
	ds_read_b128 v[132:135], v132 offset:3072
	s_add_u32 s48, s60, 0x84000
	s_addc_u32 s49, s61, 0
	s_add_u32 s64, s60, 0x86000
	s_addc_u32 s65, s61, 0
	s_cmp_eq_u32 s71, 28
	s_cselect_b32 s61, s0, s63
	s_cselect_b32 s60, s1, s62
	ds_read_b128 v[136:139], v237
	ds_read_b128 v[140:143], v237 offset:1024
	ds_read_b128 v[152:155], v237 offset:2048
	ds_read_b128 v[156:159], v237 offset:3072
	ds_read_b128 v[160:163], v237 offset:4096
	ds_read_b128 v[164:167], v237 offset:5120
	ds_read_b128 v[168:171], v237 offset:6144
	ds_read_b128 v[172:175], v237 offset:7168
	s_waitcnt lgkmcnt(8)
	s_waitcnt vmcnt(10)
	s_barrier
	s_waitcnt lgkmcnt(0)
	s_waitcnt lgkmcnt(7)
	v_mfma_f32_16x16x32_bf16 v[148:151], v[120:123], v[136:139], v[148:151]
	v_mfma_f32_16x16x32_bf16 v[144:147], v[128:131], v[136:139], v[144:147]
	s_waitcnt lgkmcnt(5)
	v_mfma_f32_16x16x32_bf16 v[108:111], v[120:123], v[152:155], v[108:111]
	v_mfma_f32_16x16x32_bf16 v[104:107], v[128:131], v[152:155], v[104:107]
	s_waitcnt lgkmcnt(3)
	v_mfma_f32_16x16x32_bf16 v[92:95], v[120:123], v[160:163], v[92:95]
	v_mfma_f32_16x16x32_bf16 v[88:91], v[128:131], v[160:163], v[88:91]
	s_waitcnt lgkmcnt(1)
	v_mfma_f32_16x16x32_bf16 v[76:79], v[120:123], v[168:171], v[76:79]
	v_mfma_f32_16x16x32_bf16 v[72:75], v[128:131], v[168:171], v[72:75]
	v_mfma_f32_16x16x32_bf16 v[148:151], v[124:127], v[140:143], v[148:151]
	v_mfma_f32_16x16x32_bf16 v[144:147], v[132:135], v[140:143], v[144:147]
	v_mfma_f32_16x16x32_bf16 v[108:111], v[124:127], v[156:159], v[108:111]
	v_mfma_f32_16x16x32_bf16 v[104:107], v[132:135], v[156:159], v[104:107]
	v_mfma_f32_16x16x32_bf16 v[92:95], v[124:127], v[164:167], v[92:95]
	v_mfma_f32_16x16x32_bf16 v[88:91], v[132:135], v[164:167], v[88:91]
	s_waitcnt lgkmcnt(0)
	v_mfma_f32_16x16x32_bf16 v[76:79], v[124:127], v[172:175], v[76:79]
	v_mfma_f32_16x16x32_bf16 v[72:75], v[132:135], v[172:175], v[72:75]
	s_barrier
	v_add_u32_e32 v200, 0x14000, v236
	ds_read_b128 v[176:179], v200
	ds_read_b128 v[180:183], v200 offset:1024
	ds_read_b128 v[184:187], v200 offset:2048
	ds_read_b128 v[200:203], v200 offset:3072
	s_cselect_b32 s64, s55, s69
	s_cselect_b32 s65, s53, s70
	s_mov_b32 m0, s24
	s_nop 0
	global_load_lds_dwordx4 v188, s[64:65]
	s_add_u32 s48, s64, 0x2000
	s_addc_u32 s49, s65, 0
	s_mov_b32 m0, s25
	s_nop 0
	global_load_lds_dwordx4 v188, s[48:49]
	s_waitcnt vmcnt(10)
	s_barrier
	s_waitcnt lgkmcnt(0)
	s_waitcnt lgkmcnt(3)
	v_mfma_f32_16x16x32_bf16 v[116:119], v[176:179], v[136:139], v[116:119]
	s_waitcnt lgkmcnt(1)
	v_mfma_f32_16x16x32_bf16 v[112:115], v[184:187], v[136:139], v[112:115]
	v_mfma_f32_16x16x32_bf16 v[100:103], v[176:179], v[152:155], v[100:103]
	v_mfma_f32_16x16x32_bf16 v[96:99], v[184:187], v[152:155], v[96:99]
	v_mfma_f32_16x16x32_bf16 v[84:87], v[176:179], v[160:163], v[84:87]
	v_mfma_f32_16x16x32_bf16 v[80:83], v[184:187], v[160:163], v[80:83]
	v_mfma_f32_16x16x32_bf16 v[68:71], v[176:179], v[168:171], v[68:71]
	v_mfma_f32_16x16x32_bf16 v[64:67], v[184:187], v[168:171], v[64:67]
	v_mfma_f32_16x16x32_bf16 v[116:119], v[180:183], v[140:143], v[116:119]
	s_waitcnt lgkmcnt(0)
	v_mfma_f32_16x16x32_bf16 v[112:115], v[200:203], v[140:143], v[112:115]
	v_mfma_f32_16x16x32_bf16 v[100:103], v[180:183], v[156:159], v[100:103]
	v_mfma_f32_16x16x32_bf16 v[96:99], v[200:203], v[156:159], v[96:99]
	v_mfma_f32_16x16x32_bf16 v[84:87], v[180:183], v[164:167], v[84:87]
	v_mfma_f32_16x16x32_bf16 v[80:83], v[200:203], v[164:167], v[80:83]
	v_mfma_f32_16x16x32_bf16 v[68:71], v[180:183], v[172:175], v[68:71]
	v_mfma_f32_16x16x32_bf16 v[64:67], v[200:203], v[172:175], v[64:67]
	s_barrier
	ds_read_b128 v[136:139], v237 offset:16384
	ds_read_b128 v[140:143], v237 offset:17408
	ds_read_b128 v[152:155], v237 offset:18432
	ds_read_b128 v[156:159], v237 offset:19456
	ds_read_b128 v[160:163], v237 offset:20480
	ds_read_b128 v[164:167], v237 offset:21504
	ds_read_b128 v[168:171], v237 offset:22528
	ds_read_b128 v[172:175], v237 offset:23552
	s_mov_b32 m0, s22
	s_nop 0
	global_load_lds_dwordx4 v188, s[60:61]
	s_add_u32 s48, s60, 0x2000
	s_addc_u32 s49, s61, 0
	s_mov_b32 m0, s26
	s_nop 0
	global_load_lds_dwordx4 v188, s[48:49]
	s_barrier
	s_waitcnt lgkmcnt(0)
	s_waitcnt lgkmcnt(7)
	v_mfma_f32_16x16x32_bf16 v[60:63], v[120:123], v[136:139], v[60:63]
	v_mfma_f32_16x16x32_bf16 v[56:59], v[128:131], v[136:139], v[56:59]
	s_waitcnt lgkmcnt(5)
	v_mfma_f32_16x16x32_bf16 v[44:47], v[120:123], v[152:155], v[44:47]
	v_mfma_f32_16x16x32_bf16 v[40:43], v[128:131], v[152:155], v[40:43]
	s_waitcnt lgkmcnt(3)
	v_mfma_f32_16x16x32_bf16 v[28:31], v[120:123], v[160:163], v[28:31]
	v_mfma_f32_16x16x32_bf16 v[24:27], v[128:131], v[160:163], v[24:27]
	s_waitcnt lgkmcnt(1)
	v_mfma_f32_16x16x32_bf16 v[12:15], v[120:123], v[168:171], v[12:15]
	v_mfma_f32_16x16x32_bf16 v[8:11], v[128:131], v[168:171], v[8:11]
	v_mfma_f32_16x16x32_bf16 v[60:63], v[124:127], v[140:143], v[60:63]
	v_mfma_f32_16x16x32_bf16 v[56:59], v[132:135], v[140:143], v[56:59]
	v_mfma_f32_16x16x32_bf16 v[44:47], v[124:127], v[156:159], v[44:47]
	v_mfma_f32_16x16x32_bf16 v[40:43], v[132:135], v[156:159], v[40:43]
	v_mfma_f32_16x16x32_bf16 v[28:31], v[124:127], v[164:167], v[28:31]
	v_mfma_f32_16x16x32_bf16 v[24:27], v[132:135], v[164:167], v[24:27]
	s_waitcnt lgkmcnt(0)
	v_mfma_f32_16x16x32_bf16 v[12:15], v[124:127], v[172:175], v[12:15]
	v_mfma_f32_16x16x32_bf16 v[8:11], v[132:135], v[172:175], v[8:11]
	s_barrier
; #define PG8_STAGE(bufoff, gbase, hoff, imm) do { _Pragma("unroll") for (int _i = 0; _i < 2; ++_i) { \
;         asm volatile("s_mov_b32 m0, %0\n\ts_nop 0\n\tglobal_load_lds_dwordx4 %1, %2" \
;             :: "s"(lds0 + (unsigned)((bufoff) + _i * 8192)), "v"(voff0), "s"((const char*)(gbase) + (size_t)(hoff) + (size_t)(_i * 8192)) : "memory"); } } while (0)
; #define PG8_LDA(dst, b, h) do { _Pragma("unroll") for (int m = 0; m < 4; ++m) _Pragma("unroll") for (int k = 0; k < 2; ++k) dst[m][k] = *(const LAS bf16x8*)(lds + PG8_SA(b, h) + aoff + m * 2048 + k * 1024); } while (0)
; #define PG8_LDB(dst, b, h) do { _Pragma("unroll") for (int n = 0; n < 2; ++n) _Pragma("unroll") for (int k = 0; k < 2; ++k) dst[n][k] = *(const LAS bf16x8*)(lds + PG8_SB(b, h) + boff + n * 2048 + k * 1024); } while (0)
; #define PG8_MMA(ai, bj, At, Bt) do { __builtin_amdgcn_s_setprio(1); _Pragma("unroll") for (int m = 0; m < 4; ++m) _Pragma("unroll") for (int n = 0; n < 2; ++n) _Pragma("unroll") for (int k = 0; k < 2; ++k) \
;         acc[ai][bj][m][n] = __builtin_amdgcn_mfma_f32_16x16x32_bf16(Bt[n][k], At[m][k], acc[ai][bj][m][n], 0, 0, 0); __builtin_amdgcn_s_setprio(0); } while (0)
; #define PG8_WAIT_V(n) asm volatile("s_waitcnt vmcnt(" #n ")" ::: "memory")
; #define PG8_WAIT_L(n) asm volatile("s_waitcnt lgkmcnt(" #n ")" ::: "memory")
; #define PG8_BAR __builtin_amdgcn_s_barrier()
; #define PG8_SCHED __builtin_amdgcn_sched_barrier(0)
; template <class Epi>
; __device__ __forceinline__ void gemm_phase(LAS unsigned char* lds, const Gemm g, const StaticOrder& S, const Epi& E) {
;     ...
;             PG8_STAGE(PG8_SB(0, 1), b2, hB, 0);
;             PG8_WAIT_V(6); PG8_BAR; PG8_MMA(1, 1, At, B1); PG8_BAR;
;             PG8_LDB(B0, 1, 0); PG8_SCHED; PG8_LDA(At, 1, 0); PG8_STAGE(PG8_SA(0, 1), a2, hA, 0);
;             PG8_WAIT_L(8); PG8_BAR; PG8_WAIT_L(0); PG8_MMA(0, 0, At, B0); PG8_BAR; PG8_SCHED;
;             PG8_LDB(B1, 1, 1); PG8_STAGE(PG8_SB(1, 0), b2 + KS, 0, 0);
;             PG8_BAR; PG8_WAIT_L(0); PG8_MMA(0, 1, At, B1); PG8_BAR;
;             PG8_LDA(At, 1, 1); PG8_STAGE(PG8_SA(1, 0), a2 + KS, 0, 0);
	s_add_u32 s48, s64, 0x80000
	s_addc_u32 s49, s65, 0
	s_mov_b32 m0, s27
	s_nop 0
	global_load_lds_dwordx4 v188, s[48:49]
	s_add_u32 s48, s64, 0x82000
	s_addc_u32 s49, s65, 0
	s_mov_b32 m0, s28
	s_nop 0
	global_load_lds_dwordx4 v188, s[48:49]
	s_add_u32 s48, s60, 0x80000
	s_addc_u32 s49, s61, 0
	s_mov_b32 m0, s29
	s_nop 0
	global_load_lds_dwordx4 v188, s[48:49]
	s_add_u32 s48, s60, 0x82000
	s_addc_u32 s49, s61, 0
	s_mov_b32 m0, s30
	s_nop 0
	global_load_lds_dwordx4 v188, s[48:49]
	s_waitcnt vmcnt(12)
	s_barrier
	v_mfma_f32_16x16x32_bf16 v[52:55], v[176:179], v[136:139], v[52:55]
	v_mfma_f32_16x16x32_bf16 v[48:51], v[184:187], v[136:139], v[48:51]
	v_mfma_f32_16x16x32_bf16 v[36:39], v[176:179], v[152:155], v[36:39]
	v_mfma_f32_16x16x32_bf16 v[32:35], v[184:187], v[152:155], v[32:35]
	v_mfma_f32_16x16x32_bf16 v[20:23], v[176:179], v[160:163], v[20:23]
	v_mfma_f32_16x16x32_bf16 v[16:19], v[184:187], v[160:163], v[16:19]
	v_mfma_f32_16x16x32_bf16 v[4:7], v[176:179], v[168:171], v[4:7]
	v_mfma_f32_16x16x32_bf16 v[0:3], v[184:187], v[168:171], v[0:3]
	v_mfma_f32_16x16x32_bf16 v[52:55], v[180:183], v[140:143], v[52:55]
	v_mfma_f32_16x16x32_bf16 v[48:51], v[200:203], v[140:143], v[48:51]
	v_mfma_f32_16x16x32_bf16 v[36:39], v[180:183], v[156:159], v[36:39]
	v_mfma_f32_16x16x32_bf16 v[32:35], v[200:203], v[156:159], v[32:35]
	v_mfma_f32_16x16x32_bf16 v[20:23], v[180:183], v[164:167], v[20:23]
	v_mfma_f32_16x16x32_bf16 v[16:19], v[200:203], v[164:167], v[16:19]
	v_mfma_f32_16x16x32_bf16 v[4:7], v[180:183], v[172:175], v[4:7]
	v_mfma_f32_16x16x32_bf16 v[0:3], v[200:203], v[172:175], v[0:3]
	v_add_u32_e32 v132, 0x18000, v236
	s_barrier
	ds_read_b128 v[120:123], v132
	ds_read_b128 v[124:127], v132 offset:1024
	ds_read_b128 v[128:131], v132 offset:2048
	ds_read_b128 v[132:135], v132 offset:3072
	ds_read_b128 v[136:139], v237 offset:32768
	ds_read_b128 v[140:143], v237 offset:33792
	ds_read_b128 v[152:155], v237 offset:34816
	ds_read_b128 v[156:159], v237 offset:35840
	ds_read_b128 v[160:163], v237 offset:36864
	ds_read_b128 v[164:167], v237 offset:37888
	ds_read_b128 v[168:171], v237 offset:38912
	ds_read_b128 v[172:175], v237 offset:39936
	s_waitcnt lgkmcnt(8)
	s_waitcnt vmcnt(10)
	s_barrier
	s_waitcnt lgkmcnt(0)
	s_waitcnt lgkmcnt(7)
	v_mfma_f32_16x16x32_bf16 v[148:151], v[120:123], v[136:139], v[148:151]
	v_mfma_f32_16x16x32_bf16 v[144:147], v[128:131], v[136:139], v[144:147]
	s_waitcnt lgkmcnt(5)
	v_mfma_f32_16x16x32_bf16 v[108:111], v[120:123], v[152:155], v[108:111]
	v_mfma_f32_16x16x32_bf16 v[104:107], v[128:131], v[152:155], v[104:107]
	s_waitcnt lgkmcnt(3)
	v_mfma_f32_16x16x32_bf16 v[92:95], v[120:123], v[160:163], v[92:95]
	v_mfma_f32_16x16x32_bf16 v[88:91], v[128:131], v[160:163], v[88:91]
	s_waitcnt lgkmcnt(1)
	v_mfma_f32_16x16x32_bf16 v[76:79], v[120:123], v[168:171], v[76:79]
	v_mfma_f32_16x16x32_bf16 v[72:75], v[128:131], v[168:171], v[72:75]
	v_mfma_f32_16x16x32_bf16 v[148:151], v[124:127], v[140:143], v[148:151]
	v_mfma_f32_16x16x32_bf16 v[144:147], v[132:135], v[140:143], v[144:147]
	v_mfma_f32_16x16x32_bf16 v[108:111], v[124:127], v[156:159], v[108:111]
	v_mfma_f32_16x16x32_bf16 v[104:107], v[132:135], v[156:159], v[104:107]
	v_mfma_f32_16x16x32_bf16 v[92:95], v[124:127], v[164:167], v[92:95]
	v_mfma_f32_16x16x32_bf16 v[88:91], v[132:135], v[164:167], v[88:91]
	s_waitcnt lgkmcnt(0)
	v_mfma_f32_16x16x32_bf16 v[76:79], v[124:127], v[172:175], v[76:79]
	v_mfma_f32_16x16x32_bf16 v[72:75], v[132:135], v[172:175], v[72:75]
	s_barrier
	v_add_u32_e32 v200, 0x1c000, v236
	ds_read_b128 v[176:179], v200
	ds_read_b128 v[180:183], v200 offset:1024
	ds_read_b128 v[184:187], v200 offset:2048
	ds_read_b128 v[200:203], v200 offset:3072
	s_add_u32 s48, s64, 0x4000
	s_addc_u32 s49, s65, 0
	s_mov_b32 m0, s39
	s_nop 0
	global_load_lds_dwordx4 v188, s[48:49]
	s_add_u32 s48, s64, 0x6000
	s_addc_u32 s49, s65, 0
	s_mov_b32 m0, s40
	s_nop 0
	global_load_lds_dwordx4 v188, s[48:49]
	s_waitcnt vmcnt(10)
	s_barrier
	s_waitcnt lgkmcnt(0)
	s_waitcnt lgkmcnt(3)
	v_mfma_f32_16x16x32_bf16 v[116:119], v[176:179], v[136:139], v[116:119]
	s_waitcnt lgkmcnt(1)
	v_mfma_f32_16x16x32_bf16 v[112:115], v[184:187], v[136:139], v[112:115]
	v_mfma_f32_16x16x32_bf16 v[100:103], v[176:179], v[152:155], v[100:103]
	v_mfma_f32_16x16x32_bf16 v[96:99], v[184:187], v[152:155], v[96:99]
	v_mfma_f32_16x16x32_bf16 v[84:87], v[176:179], v[160:163], v[84:87]
	v_mfma_f32_16x16x32_bf16 v[80:83], v[184:187], v[160:163], v[80:83]
	v_mfma_f32_16x16x32_bf16 v[68:71], v[176:179], v[168:171], v[68:71]
	v_mfma_f32_16x16x32_bf16 v[64:67], v[184:187], v[168:171], v[64:67]
	v_mfma_f32_16x16x32_bf16 v[116:119], v[180:183], v[140:143], v[116:119]
	s_waitcnt lgkmcnt(0)
	v_mfma_f32_16x16x32_bf16 v[112:115], v[200:203], v[140:143], v[112:115]
	v_mfma_f32_16x16x32_bf16 v[100:103], v[180:183], v[156:159], v[100:103]
	v_mfma_f32_16x16x32_bf16 v[96:99], v[200:203], v[156:159], v[96:99]
	v_mfma_f32_16x16x32_bf16 v[84:87], v[180:183], v[164:167], v[84:87]
	v_mfma_f32_16x16x32_bf16 v[80:83], v[200:203], v[164:167], v[80:83]
	v_mfma_f32_16x16x32_bf16 v[68:71], v[180:183], v[172:175], v[68:71]
	v_mfma_f32_16x16x32_bf16 v[64:67], v[200:203], v[172:175], v[64:67]
	s_barrier
	ds_read_b128 v[136:139], v237 offset:49152
	ds_read_b128 v[140:143], v237 offset:50176
	ds_read_b128 v[152:155], v237 offset:51200
	ds_read_b128 v[156:159], v237 offset:52224
	ds_read_b128 v[160:163], v237 offset:53248
	ds_read_b128 v[164:167], v237 offset:54272
	ds_read_b128 v[168:171], v237 offset:55296
	ds_read_b128 v[172:175], v237 offset:56320
	s_add_u32 s48, s60, 0x4000
	s_addc_u32 s49, s61, 0
	s_mov_b32 m0, s41
	s_nop 0
	global_load_lds_dwordx4 v188, s[48:49]
	s_add_u32 s48, s60, 0x6000
	s_addc_u32 s49, s61, 0
	s_mov_b32 m0, s42
	s_nop 0
	global_load_lds_dwordx4 v188, s[48:49]
	s_barrier
; template <class Epi>
; __device__ __forceinline__ void gemm_phase(LAS unsigned char* lds, const Gemm g, const StaticOrder& S, const Epi& E) {
;     ...
;             PG8_BAR; PG8_WAIT_L(0); PG8_MMA(1, 0, At, B0); PG8_BAR; PG8_SCHED;
;             PG8_STAGE(PG8_SB(1, 1), b2 + KS, hB, 0);
;             PG8_WAIT_V(6); PG8_BAR; PG8_MMA(1, 1, At, B1); PG8_BAR;
;         }
;     __device__ __forceinline__ void operator()(f32x4 (&acc)[2][2][4][2], const Unit& u, int wr, int wc, int fr, int fq, LAS unsigned char*) const {
;         const int b = u.pm >> 6;
;         const int col0 = u.pn * BM + wc * 32 + 8 * fq;
;         const size_t off0 = (size_t)(u.pm * BM + wr * 64 + fr) * D + col0;
;         f32x4 sc[2][2];
; #pragma unroll
;         for (int bj = 0; bj < 2; ++bj)
; #pragma unroll
;             for (int n = 0; n < 2; ++n) { f32x4 gt = *(const f32x4*)(gate + (size_t)b * MODW + col0 + bj * HALF + n * 4); sc[bj][n] = gt + 1.0f;
;                 if (cs) sc[bj][n] *= *(const f32x4*)(cs + col0 + bj * HALF + n * 4); }
;         if (IN_F32) {
; #pragma unroll
;             for (int ai = 0; ai < 2; ++ai) {
;                 f32x4 r[4][2][2];
; #pragma unroll
;                 for (int m = 0; m < 4; ++m)
; #pragma unroll
;                     for (int bj = 0; bj < 2; ++bj)
; #pragma unroll
;                         for (int n = 0; n < 2; ++n) r[m][bj][n] = *(const f32x4*)((const float*)in + off0 + (size_t)(ai * HALF + m * 16) * D + bj * HALF + n * 4);
; #pragma unroll
;                 for (int m = 0; m < 4; ++m)
; #pragma unroll
;                     for (int bj = 0; bj < 2; ++bj) { const f32x4 r0 = r[m][bj][0] + sc[bj][0] * acc[ai][bj][m][0], r1 = r[m][bj][1] + sc[bj][1] * acc[ai][bj][m][1];
;                         u32x4 w; w.x = cvt_pk_bf16(r0[0], r0[1]); w.y = cvt_pk_bf16(r0[2], r0[3]); w.z = cvt_pk_bf16(r1[0], r1[1]); w.w = cvt_pk_bf16(r1[2], r1[3]);
;                         *(u32x4*)(out + off0 + (size_t)(ai * HALF + m * 16) * D + bj * HALF) = w; }
;                 asm volatile("" ::: "memory");
;             }
;         } else {
;             u32x4 xb[2][4][2];
; #pragma unroll
;             for (int ai = 0; ai < 2; ++ai)
; #pragma unroll
;                 for (int m = 0; m < 4; ++m)
; #pragma unroll
;                     for (int bj = 0; bj < 2; ++bj) xb[ai][m][bj] = *(const u32x4*)((const bf16_t*)in + off0 + (size_t)(ai * HALF + m * 16) * D + bj * HALF);
	s_waitcnt lgkmcnt(0)
	s_waitcnt lgkmcnt(7)
	v_mfma_f32_16x16x32_bf16 v[60:63], v[120:123], v[136:139], v[60:63]
	v_mfma_f32_16x16x32_bf16 v[56:59], v[128:131], v[136:139], v[56:59]
	s_waitcnt lgkmcnt(5)
	v_mfma_f32_16x16x32_bf16 v[44:47], v[120:123], v[152:155], v[44:47]
	v_mfma_f32_16x16x32_bf16 v[40:43], v[128:131], v[152:155], v[40:43]
	s_waitcnt lgkmcnt(3)
	v_mfma_f32_16x16x32_bf16 v[28:31], v[120:123], v[160:163], v[28:31]
	v_mfma_f32_16x16x32_bf16 v[24:27], v[128:131], v[160:163], v[24:27]
	s_waitcnt lgkmcnt(1)
	v_mfma_f32_16x16x32_bf16 v[12:15], v[120:123], v[168:171], v[12:15]
	v_mfma_f32_16x16x32_bf16 v[8:11], v[128:131], v[168:171], v[8:11]
	v_mfma_f32_16x16x32_bf16 v[60:63], v[124:127], v[140:143], v[60:63]
	v_mfma_f32_16x16x32_bf16 v[56:59], v[132:135], v[140:143], v[56:59]
	v_mfma_f32_16x16x32_bf16 v[44:47], v[124:127], v[156:159], v[44:47]
	v_mfma_f32_16x16x32_bf16 v[40:43], v[132:135], v[156:159], v[40:43]
	v_mfma_f32_16x16x32_bf16 v[28:31], v[124:127], v[164:167], v[28:31]
	v_mfma_f32_16x16x32_bf16 v[24:27], v[132:135], v[164:167], v[24:27]
	s_waitcnt lgkmcnt(0)
	v_mfma_f32_16x16x32_bf16 v[12:15], v[124:127], v[172:175], v[12:15]
	v_mfma_f32_16x16x32_bf16 v[8:11], v[132:135], v[172:175], v[8:11]
	s_barrier
	s_add_u32 s48, s64, 0x84000
	s_addc_u32 s49, s65, 0
	s_mov_b32 m0, s43
	s_nop 0
	global_load_lds_dwordx4 v188, s[48:49]
	s_add_u32 s48, s64, 0x86000
	s_addc_u32 s49, s65, 0
	s_mov_b32 m0, s66
	s_nop 0
	global_load_lds_dwordx4 v188, s[48:49]
	s_add_u32 s48, s60, 0x84000
	s_addc_u32 s49, s61, 0
	s_mov_b32 m0, s67
	s_nop 0
	global_load_lds_dwordx4 v188, s[48:49]
	s_add_u32 s48, s60, 0x86000
	s_addc_u32 s49, s61, 0
	s_mov_b32 m0, s68
	s_nop 0
	global_load_lds_dwordx4 v188, s[48:49]
	s_waitcnt vmcnt(12)
	s_barrier
	v_mfma_f32_16x16x32_bf16 v[52:55], v[176:179], v[136:139], v[52:55]
	v_mfma_f32_16x16x32_bf16 v[48:51], v[184:187], v[136:139], v[48:51]
	v_mfma_f32_16x16x32_bf16 v[36:39], v[176:179], v[152:155], v[36:39]
	v_mfma_f32_16x16x32_bf16 v[32:35], v[184:187], v[152:155], v[32:35]
	v_mfma_f32_16x16x32_bf16 v[20:23], v[176:179], v[160:163], v[20:23]
	v_mfma_f32_16x16x32_bf16 v[16:19], v[184:187], v[160:163], v[16:19]
	v_mfma_f32_16x16x32_bf16 v[4:7], v[176:179], v[168:171], v[4:7]
	v_mfma_f32_16x16x32_bf16 v[0:3], v[184:187], v[168:171], v[0:3]
	v_mfma_f32_16x16x32_bf16 v[52:55], v[180:183], v[140:143], v[52:55]
	v_mfma_f32_16x16x32_bf16 v[48:51], v[200:203], v[140:143], v[48:51]
	v_mfma_f32_16x16x32_bf16 v[36:39], v[180:183], v[156:159], v[36:39]
	v_mfma_f32_16x16x32_bf16 v[32:35], v[200:203], v[156:159], v[32:35]
	v_mfma_f32_16x16x32_bf16 v[20:23], v[180:183], v[164:167], v[20:23]
	v_mfma_f32_16x16x32_bf16 v[16:19], v[200:203], v[164:167], v[16:19]
	v_mfma_f32_16x16x32_bf16 v[4:7], v[180:183], v[172:175], v[4:7]
	v_mfma_f32_16x16x32_bf16 v[0:3], v[200:203], v[172:175], v[0:3]
	s_add_i32 s71, s71, 2
	s_add_u32 s69, s69, 0x8000
	s_addc_u32 s70, s70, 0
	s_cmp_gt_u32 s71, 29
	s_mov_b64 s[60:61], s[62:63]
	s_barrier
	s_cbranch_scc0 .LBB0_610
	s_ashr_i32 s0, s50, 6
	s_mul_hi_i32 s1, s0, 0xc000
	s_mul_i32 s0, s0, 0xc000
	v_lshl_or_b32 v128, s51, 8, v234
	s_add_u32 s0, s37, s0
	v_ashrrev_i32_e32 v129, 31, v128
	s_addc_u32 s1, s38, s1
	v_lshl_add_u64 v[130:131], v[128:129], 2, s[0:1]
	global_load_dwordx4 v[120:123], v[130:131], off offset:16
	global_load_dwordx4 v[124:127], v[130:131], off
	s_mov_b32 s51, s52
	s_mov_b64 s[62:63], s[58:59]
	s_mov_b64 s[60:61], s[56:57]
	s_waitcnt vmcnt(1)
	v_pk_add_f32 v[210:211], v[122:123], 1.0 op_sel_hi:[1,0]
	s_waitcnt vmcnt(0)
	v_pk_add_f32 v[214:215], v[126:127], 1.0 op_sel_hi:[1,0]
	v_pk_add_f32 v[212:213], v[124:125], 1.0 op_sel_hi:[1,0]
	v_pk_add_f32 v[208:209], v[120:121], 1.0 op_sel_hi:[1,0]
	global_load_dwordx4 v[120:123], v[130:131], off offset:528
	global_load_dwordx4 v[124:127], v[130:131], off offset:512
	s_waitcnt vmcnt(1)
	v_pk_add_f32 v[200:201], v[120:121], 1.0 op_sel_hi:[1,0]
	v_lshl_add_u32 v120, s50, 8, v233
	v_ashrrev_i32_e32 v121, 31, v120
	v_lshlrev_b64 v[120:121], 11, v[120:121]
	v_lshl_add_u64 v[120:121], v[120:121], 0, v[128:129]
	v_lshlrev_b64 v[216:217], 1, v[120:121]
	v_lshl_add_u64 v[120:121], s[8:9], 0, v[216:217]
	global_load_dwordx4 v[238:241], v[120:121], off
	global_load_dwordx4 v[184:187], v[120:121], off offset:256
	v_pk_add_f32 v[202:203], v[122:123], 1.0 op_sel_hi:[1,0]
	v_add_co_u32_e32 v122, vcc, s45, v120
	s_waitcnt vmcnt(2)
	v_pk_add_f32 v[206:207], v[126:127], 1.0 op_sel_hi:[1,0]
	v_addc_co_u32_e32 v123, vcc, 0, v121, vcc
	global_load_dwordx4 v[180:183], v[122:123], off
	global_load_dwordx4 v[176:179], v[122:123], off offset:256
	v_add_co_u32_e32 v122, vcc, s36, v120
	v_pk_add_f32 v[204:205], v[124:125], 1.0 op_sel_hi:[1,0]
	s_nop 0
	v_addc_co_u32_e32 v123, vcc, 0, v121, vcc
	global_load_dwordx4 v[172:175], v[122:123], off
	global_load_dwordx4 v[168:171], v[122:123], off offset:256
	v_add_co_u32_e32 v122, vcc, s23, v120
	s_mov_b32 s50, s54
	s_nop 0
	v_addc_co_u32_e32 v123, vcc, 0, v121, vcc
	global_load_dwordx4 v[164:167], v[122:123], off
	global_load_dwordx4 v[160:163], v[122:123], off offset:256
	v_add_co_u32_e32 v122, vcc, s93, v120
	s_waitcnt vmcnt(7)
; __device__ __forceinline__ unsigned cvt_pk_bf16(float lo, float hi) { unsigned r; asm volatile("v_cvt_pk_bf16_f32 %0, %1, %2" : "=v"(r) : "v"(lo), "v"(hi)); return r; }
;     __device__ __forceinline__ void operator()(f32x4 (&acc)[2][2][4][2], const Unit& u, int wr, int wc, int fr, int fq, LAS unsigned char*) const {
;     ...
;             u32x4 xb[2][4][2];
; #pragma unroll
;             for (int ai = 0; ai < 2; ++ai)
; #pragma unroll
;                 for (int m = 0; m < 4; ++m)
; #pragma unroll
;                     for (int bj = 0; bj < 2; ++bj) xb[ai][m][bj] = *(const u32x4*)((const bf16_t*)in + off0 + (size_t)(ai * HALF + m * 16) * D + bj * HALF);
; #pragma unroll
;             for (int ai = 0; ai < 2; ++ai)
; #pragma unroll
;                 for (int m = 0; m < 4; ++m)
; #pragma unroll
;                     for (int bj = 0; bj < 2; ++bj) { const u32x4 x = xb[ai][m][bj];
;                         f32x4 r0 = (f32x4){__uint_as_float(x.x << 16), __uint_as_float(x.x & 0xffff0000u), __uint_as_float(x.y << 16), __uint_as_float(x.y & 0xffff0000u)};
;                         f32x4 r1 = (f32x4){__uint_as_float(x.z << 16), __uint_as_float(x.z & 0xffff0000u), __uint_as_float(x.w << 16), __uint_as_float(x.w & 0xffff0000u)};
;                         r0 += sc[bj][0] * acc[ai][bj][m][0]; r1 += sc[bj][1] * acc[ai][bj][m][1];
;                         u32x4 w; w.x = cvt_pk_bf16(r0[0], r0[1]); w.y = cvt_pk_bf16(r0[2], r0[3]); w.z = cvt_pk_bf16(r1[0], r1[1]); w.w = cvt_pk_bf16(r1[2], r1[3]);
;                         *(u32x4*)(out + off0 + (size_t)(ai * HALF + m * 16) * D + bj * HALF) = w; }
	v_lshlrev_b32_e32 v230, 16, v238
	v_addc_co_u32_e32 v123, vcc, 0, v121, vcc
	global_load_dwordx4 v[156:159], v[122:123], off
	global_load_dwordx4 v[152:155], v[122:123], off offset:256
	v_add_co_u32_e32 v122, vcc, s33, v120
	v_and_b32_e32 v231, 0xffff0000, v238
	s_nop 0
	v_addc_co_u32_e32 v123, vcc, 0, v121, vcc
	global_load_dwordx4 v[140:143], v[122:123], off
	global_load_dwordx4 v[136:139], v[122:123], off offset:256
	v_add_co_u32_e32 v122, vcc, s18, v120
	v_lshlrev_b32_e32 v242, 16, v240
	s_nop 0
	v_addc_co_u32_e32 v123, vcc, 0, v121, vcc
	global_load_dwordx4 v[132:135], v[122:123], off
	global_load_dwordx4 v[128:131], v[122:123], off offset:256
	v_add_co_u32_e32 v120, vcc, s19, v120
	v_and_b32_e32 v243, 0xffff0000, v240
	s_nop 0
	v_addc_co_u32_e32 v121, vcc, 0, v121, vcc
	global_load_dwordx4 v[124:127], v[120:121], off
	s_nop 0
	global_load_dwordx4 v[120:123], v[120:121], off offset:256
	v_lshlrev_b32_e32 v238, 16, v239
	v_and_b32_e32 v239, 0xffff0000, v239
	v_lshlrev_b32_e32 v240, 16, v241
	v_and_b32_e32 v241, 0xffff0000, v241
	v_pk_fma_f32 v[148:149], v[148:149], v[212:213], v[230:231]
	v_pk_fma_f32 v[144:145], v[144:145], v[208:209], v[242:243]
	v_pk_fma_f32 v[150:151], v[150:151], v[214:215], v[238:239]
	v_pk_fma_f32 v[230:231], v[146:147], v[210:211], v[240:241]
	v_cvt_pk_bf16_f32 v146, v148, v149
	v_cvt_pk_bf16_f32 v147, v150, v151
	v_cvt_pk_bf16_f32 v148, v144, v145
	v_lshl_add_u64 v[144:145], s[10:11], 0, v[216:217]
	v_cvt_pk_bf16_f32 v149, v230, v231
	global_store_dwordx4 v[144:145], v[146:149], off
	s_waitcnt vmcnt(15)
	v_lshlrev_b32_e32 v150, 16, v186
	v_and_b32_e32 v151, 0xffff0000, v186
	v_lshlrev_b32_e32 v146, 16, v184
	v_and_b32_e32 v147, 0xffff0000, v184
	v_lshlrev_b32_e32 v148, 16, v185
	v_and_b32_e32 v149, 0xffff0000, v185
	v_lshlrev_b32_e32 v184, 16, v187
	v_and_b32_e32 v185, 0xffff0000, v187
	v_pk_fma_f32 v[118:119], v[118:119], v[206:207], v[148:149]
	v_pk_fma_f32 v[116:117], v[116:117], v[204:205], v[146:147]
	v_pk_fma_f32 v[146:147], v[114:115], v[202:203], v[184:185]
	v_pk_fma_f32 v[114:115], v[112:113], v[200:201], v[150:151]
	v_cvt_pk_bf16_f32 v112, v116, v117
	v_cvt_pk_bf16_f32 v113, v118, v119
	s_waitcnt vmcnt(14)
	v_lshlrev_b32_e32 v116, 16, v182
	v_cvt_pk_bf16_f32 v114, v114, v115
	v_cvt_pk_bf16_f32 v115, v146, v147
	global_store_dwordx4 v[144:145], v[112:115], off offset:256
	v_and_b32_e32 v117, 0xffff0000, v182
	v_lshlrev_b32_e32 v118, 16, v183
	v_lshlrev_b32_e32 v112, 16, v180
	v_and_b32_e32 v113, 0xffff0000, v180
	v_and_b32_e32 v119, 0xffff0000, v183
	v_pk_fma_f32 v[108:109], v[108:109], v[212:213], v[112:113]
	v_lshlrev_b32_e32 v114, 16, v181
	v_and_b32_e32 v115, 0xffff0000, v181
	v_pk_fma_f32 v[112:113], v[106:107], v[210:211], v[118:119]
	v_pk_fma_f32 v[106:107], v[104:105], v[208:209], v[116:117]
	v_cvt_pk_bf16_f32 v104, v108, v109
	v_add_co_u32_e32 v108, vcc, s45, v144
	v_pk_fma_f32 v[110:111], v[110:111], v[214:215], v[114:115]
	s_nop 0
	v_addc_co_u32_e32 v109, vcc, 0, v145, vcc
	v_cvt_pk_bf16_f32 v105, v110, v111
	v_cvt_pk_bf16_f32 v106, v106, v107
	v_cvt_pk_bf16_f32 v107, v112, v113
	global_store_dwordx4 v[108:109], v[104:107], off
	s_waitcnt vmcnt(15)
	v_lshlrev_b32_e32 v110, 16, v178
	v_and_b32_e32 v111, 0xffff0000, v178
	v_lshlrev_b32_e32 v104, 16, v176
	v_and_b32_e32 v105, 0xffff0000, v176
	v_lshlrev_b32_e32 v106, 16, v177
	v_and_b32_e32 v107, 0xffff0000, v177
	v_lshlrev_b32_e32 v112, 16, v179
	v_and_b32_e32 v113, 0xffff0000, v179
	v_pk_fma_f32 v[102:103], v[102:103], v[206:207], v[106:107]
	v_pk_fma_f32 v[100:101], v[100:101], v[204:205], v[104:105]
	v_pk_fma_f32 v[104:105], v[98:99], v[202:203], v[112:113]
	v_pk_fma_f32 v[98:99], v[96:97], v[200:201], v[110:111]
	v_cvt_pk_bf16_f32 v96, v100, v101
	v_cvt_pk_bf16_f32 v97, v102, v103
	s_waitcnt vmcnt(14)
	v_lshlrev_b32_e32 v100, 16, v174
	v_cvt_pk_bf16_f32 v98, v98, v99
	v_cvt_pk_bf16_f32 v99, v104, v105
	global_store_dwordx4 v[108:109], v[96:99], off offset:256
	v_and_b32_e32 v101, 0xffff0000, v174
	v_lshlrev_b32_e32 v102, 16, v175
	v_lshlrev_b32_e32 v96, 16, v172
	v_and_b32_e32 v97, 0xffff0000, v172
	v_and_b32_e32 v103, 0xffff0000, v175
	v_pk_fma_f32 v[92:93], v[92:93], v[212:213], v[96:97]
	v_lshlrev_b32_e32 v98, 16, v173
	v_and_b32_e32 v99, 0xffff0000, v173
	v_pk_fma_f32 v[96:97], v[90:91], v[210:211], v[102:103]
	v_pk_fma_f32 v[90:91], v[88:89], v[208:209], v[100:101]
	v_cvt_pk_bf16_f32 v88, v92, v93
	v_add_co_u32_e32 v92, vcc, s36, v144
	v_pk_fma_f32 v[94:95], v[94:95], v[214:215], v[98:99]
	s_nop 0
	v_addc_co_u32_e32 v93, vcc, 0, v145, vcc
	v_cvt_pk_bf16_f32 v89, v94, v95
	v_cvt_pk_bf16_f32 v90, v90, v91
	v_cvt_pk_bf16_f32 v91, v96, v97
	global_store_dwordx4 v[92:93], v[88:91], off
	s_waitcnt vmcnt(15)
	v_lshlrev_b32_e32 v94, 16, v170
	v_and_b32_e32 v95, 0xffff0000, v170
	v_lshlrev_b32_e32 v88, 16, v168
	v_and_b32_e32 v89, 0xffff0000, v168
	v_lshlrev_b32_e32 v90, 16, v169
	v_and_b32_e32 v91, 0xffff0000, v169
	v_lshlrev_b32_e32 v96, 16, v171
	v_and_b32_e32 v97, 0xffff0000, v171
	v_pk_fma_f32 v[86:87], v[86:87], v[206:207], v[90:91]
	v_pk_fma_f32 v[84:85], v[84:85], v[204:205], v[88:89]
	v_pk_fma_f32 v[88:89], v[82:83], v[202:203], v[96:97]
	v_pk_fma_f32 v[82:83], v[80:81], v[200:201], v[94:95]
	v_cvt_pk_bf16_f32 v80, v84, v85
	v_cvt_pk_bf16_f32 v81, v86, v87
	s_waitcnt vmcnt(14)
; __device__ __forceinline__ unsigned cvt_pk_bf16(float lo, float hi) { unsigned r; asm volatile("v_cvt_pk_bf16_f32 %0, %1, %2" : "=v"(r) : "v"(lo), "v"(hi)); return r; }
;     __device__ __forceinline__ void operator()(f32x4 (&acc)[2][2][4][2], const Unit& u, int wr, int wc, int fr, int fq, LAS unsigned char*) const {
;     ...
;             for (int ai = 0; ai < 2; ++ai)
; #pragma unroll
;                 for (int m = 0; m < 4; ++m)
; #pragma unroll
;                     for (int bj = 0; bj < 2; ++bj) { const u32x4 x = xb[ai][m][bj];
;                         f32x4 r0 = (f32x4){__uint_as_float(x.x << 16), __uint_as_float(x.x & 0xffff0000u), __uint_as_float(x.y << 16), __uint_as_float(x.y & 0xffff0000u)};
;                         f32x4 r1 = (f32x4){__uint_as_float(x.z << 16), __uint_as_float(x.z & 0xffff0000u), __uint_as_float(x.w << 16), __uint_as_float(x.w & 0xffff0000u)};
;                         r0 += sc[bj][0] * acc[ai][bj][m][0]; r1 += sc[bj][1] * acc[ai][bj][m][1];
;                         u32x4 w; w.x = cvt_pk_bf16(r0[0], r0[1]); w.y = cvt_pk_bf16(r0[2], r0[3]); w.z = cvt_pk_bf16(r1[0], r1[1]); w.w = cvt_pk_bf16(r1[2], r1[3]);
;                         *(u32x4*)(out + off0 + (size_t)(ai * HALF + m * 16) * D + bj * HALF) = w; }
	v_lshlrev_b32_e32 v84, 16, v166
	v_cvt_pk_bf16_f32 v82, v82, v83
	v_cvt_pk_bf16_f32 v83, v88, v89
	global_store_dwordx4 v[92:93], v[80:83], off offset:256
	v_and_b32_e32 v85, 0xffff0000, v166
	v_lshlrev_b32_e32 v86, 16, v167
	v_lshlrev_b32_e32 v80, 16, v164
	v_and_b32_e32 v81, 0xffff0000, v164
	v_and_b32_e32 v87, 0xffff0000, v167
	v_pk_fma_f32 v[76:77], v[76:77], v[212:213], v[80:81]
	v_lshlrev_b32_e32 v82, 16, v165
	v_and_b32_e32 v83, 0xffff0000, v165
	v_pk_fma_f32 v[80:81], v[74:75], v[210:211], v[86:87]
	v_pk_fma_f32 v[74:75], v[72:73], v[208:209], v[84:85]
	v_cvt_pk_bf16_f32 v72, v76, v77
	v_add_co_u32_e32 v76, vcc, s23, v144
	v_pk_fma_f32 v[78:79], v[78:79], v[214:215], v[82:83]
	s_nop 0
	v_addc_co_u32_e32 v77, vcc, 0, v145, vcc
	v_cvt_pk_bf16_f32 v73, v78, v79
	v_cvt_pk_bf16_f32 v74, v74, v75
	v_cvt_pk_bf16_f32 v75, v80, v81
	global_store_dwordx4 v[76:77], v[72:75], off
	s_waitcnt vmcnt(15)
	v_lshlrev_b32_e32 v78, 16, v162
	v_and_b32_e32 v79, 0xffff0000, v162
	v_lshlrev_b32_e32 v72, 16, v160
	v_and_b32_e32 v73, 0xffff0000, v160
	v_lshlrev_b32_e32 v74, 16, v161
	v_and_b32_e32 v75, 0xffff0000, v161
	v_lshlrev_b32_e32 v80, 16, v163
	v_and_b32_e32 v81, 0xffff0000, v163
	v_pk_fma_f32 v[70:71], v[70:71], v[206:207], v[74:75]
	v_pk_fma_f32 v[68:69], v[68:69], v[204:205], v[72:73]
	v_pk_fma_f32 v[72:73], v[66:67], v[202:203], v[80:81]
	v_pk_fma_f32 v[66:67], v[64:65], v[200:201], v[78:79]
	v_cvt_pk_bf16_f32 v64, v68, v69
	v_cvt_pk_bf16_f32 v65, v70, v71
	s_waitcnt vmcnt(14)
	v_lshlrev_b32_e32 v68, 16, v158
	v_cvt_pk_bf16_f32 v66, v66, v67
	v_cvt_pk_bf16_f32 v67, v72, v73
	global_store_dwordx4 v[76:77], v[64:67], off offset:256
	v_and_b32_e32 v69, 0xffff0000, v158
	v_lshlrev_b32_e32 v70, 16, v159
	v_lshlrev_b32_e32 v64, 16, v156
	v_and_b32_e32 v65, 0xffff0000, v156
	v_and_b32_e32 v71, 0xffff0000, v159
	v_pk_fma_f32 v[60:61], v[60:61], v[212:213], v[64:65]
	v_lshlrev_b32_e32 v66, 16, v157
	v_and_b32_e32 v67, 0xffff0000, v157
	v_pk_fma_f32 v[64:65], v[58:59], v[210:211], v[70:71]
	v_pk_fma_f32 v[58:59], v[56:57], v[208:209], v[68:69]
	v_cvt_pk_bf16_f32 v56, v60, v61
	v_add_co_u32_e32 v60, vcc, s93, v144
	v_pk_fma_f32 v[62:63], v[62:63], v[214:215], v[66:67]
	s_nop 0
	v_addc_co_u32_e32 v61, vcc, 0, v145, vcc
	v_cvt_pk_bf16_f32 v57, v62, v63
	v_cvt_pk_bf16_f32 v58, v58, v59
	v_cvt_pk_bf16_f32 v59, v64, v65
	global_store_dwordx4 v[60:61], v[56:59], off
	s_waitcnt vmcnt(15)
	v_lshlrev_b32_e32 v62, 16, v154
	v_and_b32_e32 v63, 0xffff0000, v154
	v_lshlrev_b32_e32 v56, 16, v152
	v_and_b32_e32 v57, 0xffff0000, v152
	v_lshlrev_b32_e32 v58, 16, v153
	v_and_b32_e32 v59, 0xffff0000, v153
	v_lshlrev_b32_e32 v64, 16, v155
	v_and_b32_e32 v65, 0xffff0000, v155
	v_pk_fma_f32 v[54:55], v[54:55], v[206:207], v[58:59]
	v_pk_fma_f32 v[52:53], v[52:53], v[204:205], v[56:57]
	v_pk_fma_f32 v[56:57], v[50:51], v[202:203], v[64:65]
	v_pk_fma_f32 v[50:51], v[48:49], v[200:201], v[62:63]
	v_cvt_pk_bf16_f32 v48, v52, v53
	v_cvt_pk_bf16_f32 v49, v54, v55
	s_waitcnt vmcnt(14)
	v_lshlrev_b32_e32 v52, 16, v142
	v_cvt_pk_bf16_f32 v50, v50, v51
	v_cvt_pk_bf16_f32 v51, v56, v57
	global_store_dwordx4 v[60:61], v[48:51], off offset:256
	v_and_b32_e32 v53, 0xffff0000, v142
	v_lshlrev_b32_e32 v54, 16, v143
	v_lshlrev_b32_e32 v48, 16, v140
	v_and_b32_e32 v49, 0xffff0000, v140
	v_and_b32_e32 v55, 0xffff0000, v143
	v_pk_fma_f32 v[44:45], v[44:45], v[212:213], v[48:49]
	v_lshlrev_b32_e32 v50, 16, v141
	v_and_b32_e32 v51, 0xffff0000, v141
	v_pk_fma_f32 v[48:49], v[42:43], v[210:211], v[54:55]
	v_pk_fma_f32 v[42:43], v[40:41], v[208:209], v[52:53]
	v_cvt_pk_bf16_f32 v40, v44, v45
	v_add_co_u32_e32 v44, vcc, s33, v144
	v_pk_fma_f32 v[46:47], v[46:47], v[214:215], v[50:51]
	s_nop 0
	v_addc_co_u32_e32 v45, vcc, 0, v145, vcc
	v_cvt_pk_bf16_f32 v41, v46, v47
	v_cvt_pk_bf16_f32 v42, v42, v43
	v_cvt_pk_bf16_f32 v43, v48, v49
	global_store_dwordx4 v[44:45], v[40:43], off
	s_waitcnt vmcnt(15)
; __device__ __forceinline__ unsigned cvt_pk_bf16(float lo, float hi) { unsigned r; asm volatile("v_cvt_pk_bf16_f32 %0, %1, %2" : "=v"(r) : "v"(lo), "v"(hi)); return r; }
; #define PG8_WAIT_V(n) asm volatile("s_waitcnt vmcnt(" #n ")" ::: "memory")
; #define PG8_BAR __builtin_amdgcn_s_barrier()
; template <class Epi>
; __device__ __forceinline__ void gemm_phase(LAS unsigned char* lds, const Gemm g, const StaticOrder& S, const Epi& E) {
;     ...
;         if (!has_next) break;
; #pragma unroll
;         for (int a = 0; a < 2; ++a)
; #pragma unroll
;             for (int b = 0; b < 2; ++b)
; #pragma unroll
;                 for (int m = 0; m < 4; ++m)
; #pragma unroll
;                     for (int n = 0; n < 2; ++n) acc[a][b][m][n] = (f32x4){0.f, 0.f, 0.f, 0.f};
;         cur = nxt; cA = nA; cB = nB; ++ui;
;     }
;     PG8_WAIT_V(0);
;     if (wr == 0) PG8_BAR;
;     PG8_BAR;
;     __device__ __forceinline__ void operator()(f32x4 (&acc)[2][2][4][2], const Unit& u, int wr, int wc, int fr, int fq, LAS unsigned char*) const {
;     ...
;             for (int ai = 0; ai < 2; ++ai)
; #pragma unroll
;                 for (int m = 0; m < 4; ++m)
; #pragma unroll
;                     for (int bj = 0; bj < 2; ++bj) { const u32x4 x = xb[ai][m][bj];
;                         f32x4 r0 = (f32x4){__uint_as_float(x.x << 16), __uint_as_float(x.x & 0xffff0000u), __uint_as_float(x.y << 16), __uint_as_float(x.y & 0xffff0000u)};
;                         f32x4 r1 = (f32x4){__uint_as_float(x.z << 16), __uint_as_float(x.z & 0xffff0000u), __uint_as_float(x.w << 16), __uint_as_float(x.w & 0xffff0000u)};
;                         r0 += sc[bj][0] * acc[ai][bj][m][0]; r1 += sc[bj][1] * acc[ai][bj][m][1];
;                         u32x4 w; w.x = cvt_pk_bf16(r0[0], r0[1]); w.y = cvt_pk_bf16(r0[2], r0[3]); w.z = cvt_pk_bf16(r1[0], r1[1]); w.w = cvt_pk_bf16(r1[2], r1[3]);
;                         *(u32x4*)(out + off0 + (size_t)(ai * HALF + m * 16) * D + bj * HALF) = w; }
	v_lshlrev_b32_e32 v46, 16, v138
	v_and_b32_e32 v47, 0xffff0000, v138
	v_lshlrev_b32_e32 v40, 16, v136
	v_and_b32_e32 v41, 0xffff0000, v136
	v_lshlrev_b32_e32 v42, 16, v137
	v_and_b32_e32 v43, 0xffff0000, v137
	v_lshlrev_b32_e32 v48, 16, v139
	v_and_b32_e32 v49, 0xffff0000, v139
	v_pk_fma_f32 v[38:39], v[38:39], v[206:207], v[42:43]
	v_pk_fma_f32 v[36:37], v[36:37], v[204:205], v[40:41]
	v_pk_fma_f32 v[40:41], v[34:35], v[202:203], v[48:49]
	v_pk_fma_f32 v[34:35], v[32:33], v[200:201], v[46:47]
	v_cvt_pk_bf16_f32 v32, v36, v37
	v_cvt_pk_bf16_f32 v33, v38, v39
	s_waitcnt vmcnt(14)
	v_lshlrev_b32_e32 v36, 16, v134
	v_cvt_pk_bf16_f32 v34, v34, v35
	v_cvt_pk_bf16_f32 v35, v40, v41
	global_store_dwordx4 v[44:45], v[32:35], off offset:256
	v_and_b32_e32 v37, 0xffff0000, v134
	v_lshlrev_b32_e32 v38, 16, v135
	v_lshlrev_b32_e32 v32, 16, v132
	v_and_b32_e32 v33, 0xffff0000, v132
	v_and_b32_e32 v39, 0xffff0000, v135
	v_pk_fma_f32 v[28:29], v[28:29], v[212:213], v[32:33]
	v_lshlrev_b32_e32 v34, 16, v133
	v_and_b32_e32 v35, 0xffff0000, v133
	v_pk_fma_f32 v[32:33], v[26:27], v[210:211], v[38:39]
	v_pk_fma_f32 v[26:27], v[24:25], v[208:209], v[36:37]
	v_cvt_pk_bf16_f32 v24, v28, v29
	v_add_co_u32_e32 v28, vcc, s18, v144
	v_pk_fma_f32 v[30:31], v[30:31], v[214:215], v[34:35]
	s_nop 0
	v_addc_co_u32_e32 v29, vcc, 0, v145, vcc
	v_cvt_pk_bf16_f32 v25, v30, v31
	v_cvt_pk_bf16_f32 v26, v26, v27
	v_cvt_pk_bf16_f32 v27, v32, v33
	global_store_dwordx4 v[28:29], v[24:27], off
	s_waitcnt vmcnt(15)
	v_lshlrev_b32_e32 v30, 16, v130
	v_and_b32_e32 v31, 0xffff0000, v130
	v_lshlrev_b32_e32 v24, 16, v128
	v_and_b32_e32 v25, 0xffff0000, v128
	v_lshlrev_b32_e32 v26, 16, v129
	v_and_b32_e32 v27, 0xffff0000, v129
	v_lshlrev_b32_e32 v32, 16, v131
	v_and_b32_e32 v33, 0xffff0000, v131
	v_pk_fma_f32 v[22:23], v[22:23], v[206:207], v[26:27]
	v_pk_fma_f32 v[20:21], v[20:21], v[204:205], v[24:25]
	v_pk_fma_f32 v[24:25], v[18:19], v[202:203], v[32:33]
	v_pk_fma_f32 v[18:19], v[16:17], v[200:201], v[30:31]
	v_cvt_pk_bf16_f32 v16, v20, v21
	v_cvt_pk_bf16_f32 v17, v22, v23
	s_waitcnt vmcnt(14)
	v_lshlrev_b32_e32 v20, 16, v126
	v_cvt_pk_bf16_f32 v18, v18, v19
	v_cvt_pk_bf16_f32 v19, v24, v25
	global_store_dwordx4 v[28:29], v[16:19], off offset:256
	v_and_b32_e32 v21, 0xffff0000, v126
	v_lshlrev_b32_e32 v22, 16, v127
	v_lshlrev_b32_e32 v16, 16, v124
	v_and_b32_e32 v17, 0xffff0000, v124
	v_and_b32_e32 v23, 0xffff0000, v127
	v_pk_fma_f32 v[12:13], v[12:13], v[212:213], v[16:17]
	v_lshlrev_b32_e32 v18, 16, v125
	v_and_b32_e32 v19, 0xffff0000, v125
	v_pk_fma_f32 v[16:17], v[10:11], v[210:211], v[22:23]
	v_pk_fma_f32 v[10:11], v[8:9], v[208:209], v[20:21]
	v_cvt_pk_bf16_f32 v8, v12, v13
	v_add_co_u32_e32 v12, vcc, s19, v144
	v_pk_fma_f32 v[14:15], v[14:15], v[214:215], v[18:19]
	s_nop 0
	v_addc_co_u32_e32 v13, vcc, 0, v145, vcc
	v_cvt_pk_bf16_f32 v9, v14, v15
	v_cvt_pk_bf16_f32 v10, v10, v11
	v_cvt_pk_bf16_f32 v11, v16, v17
	global_store_dwordx4 v[12:13], v[8:11], off
	s_waitcnt vmcnt(15)
	v_lshlrev_b32_e32 v14, 16, v122
	v_and_b32_e32 v15, 0xffff0000, v122
	v_lshlrev_b32_e32 v8, 16, v120
	v_and_b32_e32 v9, 0xffff0000, v120
	v_lshlrev_b32_e32 v16, 16, v123
	v_and_b32_e32 v17, 0xffff0000, v123
	v_lshlrev_b32_e32 v10, 16, v121
	v_and_b32_e32 v11, 0xffff0000, v121
	v_pk_fma_f32 v[4:5], v[4:5], v[204:205], v[8:9]
	v_pk_fma_f32 v[8:9], v[2:3], v[202:203], v[16:17]
	v_pk_fma_f32 v[2:3], v[0:1], v[200:201], v[14:15]
	s_and_b64 vcc, exec, s[4:5]
	v_pk_fma_f32 v[6:7], v[6:7], v[206:207], v[10:11]
	v_cvt_pk_bf16_f32 v0, v4, v5
	s_nop 0
	v_cvt_pk_bf16_f32 v1, v6, v7
	v_cvt_pk_bf16_f32 v2, v2, v3
	v_cvt_pk_bf16_f32 v3, v8, v9
	global_store_dwordx4 v[12:13], v[0:3], off offset:256
	s_cbranch_vccz .LBB0_603
	s_waitcnt vmcnt(0)
	s_cmpk_gt_u32 s16, 0xff
	v_readlane_b32 s38, v255, 44
	s_movk_i32 s30, 0x7ff
	s_cbranch_scc1 .LBB0_614
	s_barrier

; #define PG8_STAGE(bufoff, gbase, hoff, imm) do { _Pragma("unroll") for (int _i = 0; _i < 2; ++_i) { \
;         asm volatile("s_mov_b32 m0, %0\n\ts_nop 0\n\tglobal_load_lds_dwordx4 %1, %2" \
;             :: "s"(lds0 + (unsigned)((bufoff) + _i * 8192)), "v"(voff0), "s"((const char*)(gbase) + (size_t)(hoff) + (size_t)(_i * 8192)) : "memory"); } } while (0)
; #define PG8_WAIT_V(n) asm volatile("s_waitcnt vmcnt(" #n ")" ::: "memory")
; #define PG8_BAR __builtin_amdgcn_s_barrier()
; template <class Epi>
; __device__ __forceinline__ void gemm_phase(LAS unsigned char* lds, const Gemm g, const StaticOrder& S, const Epi& E) {
;     ...
;     const char* cA = (const char*)g.A + (size_t)cur.pm * tstepA + (size_t)(cur.pn >> g.gshift) * g.gstride; const char* cB = (const char*)g.Bt + (size_t)cur.pn * tstepB;
;     PG8_STAGE(PG8_SB(0, 0), cB, 0, 0); PG8_STAGE(PG8_SA(0, 0), cA, 0, 0); PG8_STAGE(PG8_SB(0, 1), cB, hB, 0); PG8_STAGE(PG8_SA(0, 1), cA, hA, 0);
;     if (wr == 1) PG8_BAR;
;     PG8_WAIT_V(4); PG8_BAR;
;     PG8_STAGE(PG8_SB(1, 0), cB + KS, 0, 0); PG8_STAGE(PG8_SA(1, 0), cA + KS, 0, 0); PG8_STAGE(PG8_SB(1, 1), cB + KS, hB, 0);
;     PG8_WAIT_V(6); PG8_BAR;
.LBB0_848:
	s_add_u32 s52, s8, 0x29c30000
	s_addc_u32 s53, s9, 0
	s_cmp_eq_u32 s17, 0
	s_cselect_b64 s[4:5], -1, 0
	s_and_b64 s[4:5], s[2:3], s[4:5]
	s_add_u32 s6, s8, 0x31c34000
	s_addc_u32 s7, s9, 0
	s_and_b64 s[4:5], s[4:5], exec
	s_cselect_b32 s55, s7, s53
	s_cselect_b32 s54, s6, s52
	s_add_u32 s4, s8, s16
	s_addc_u32 s5, s9, 0
	s_add_u32 s39, s4, 0xa60a000
	v_lshrrev_b32_e32 v2, 1, v0
	s_addc_u32 s40, s5, 0
	v_and_b32_e32 v2, 24, v2
	s_lshl_b32 s0, s0, 5
	v_and_b32_e32 v1, 15, v0
	v_lshlrev_b32_e32 v3, 1, v2
	v_lshlrev_b32_e32 v0, 2, v0
	s_and_b32 s4, s0, 0x60
	v_lshl_or_b32 v233, s1, 6, v1
	v_lshl_or_b32 v1, v1, 6, v3
	s_lshl_b32 s1, s1, 13
	v_and_b32_e32 v0, 32, v0
	s_lshl_b32 s0, s4, 7
	s_add_i32 s41, s25, 0x18000
	v_bitop3_b32 v3, v1, s1, v0 bitop3:0xde
	v_bitop3_b32 v0, v1, s0, v0 bitop3:0xde
	s_add_u32 s0, s58, 0x4000
	s_addc_u32 s1, s59, 0
	s_add_i32 s42, s25, 0x1a000
	s_waitcnt vmcnt(4)
	s_barrier
	s_mov_b32 m0, s41
	s_nop 0
	global_load_lds_dwordx4 v188, s[0:1]
	s_add_u32 s0, s58, 0x6000
	s_addc_u32 s1, s59, 0
	s_add_i32 s43, s25, 0x8000
	s_mov_b32 m0, s42
	s_nop 0
	global_load_lds_dwordx4 v188, s[0:1]
	s_add_u32 s0, s56, 0x4000
	s_addc_u32 s1, s57, 0
	s_add_i32 s62, s25, 0xa000
	s_mov_b32 m0, s43
	s_nop 0
	global_load_lds_dwordx4 v188, s[0:1]
	s_add_u32 s0, s56, 0x6000
	s_addc_u32 s1, s57, 0
	s_add_i32 s63, s25, 0x1c000
	s_mov_b32 m0, s62
	s_nop 0
	global_load_lds_dwordx4 v188, s[0:1]
	s_add_u32 s0, s58, 0x164000
	s_addc_u32 s1, s59, 0
	s_add_i32 s64, s25, 0x1e000
	s_mov_b32 m0, s63
	s_nop 0
	global_load_lds_dwordx4 v188, s[0:1]
	s_add_u32 s0, s58, 0x166000
	s_addc_u32 s1, s59, 0
	s_mov_b32 m0, s64
	s_nop 0
	global_load_lds_dwordx4 v188, s[0:1]
	s_add_u32 s0, s56, 0x164000
	s_addc_u32 s1, s57, 0
	s_add_i32 s38, s25, 0xc000
	s_mov_b32 m0, s38
	s_nop 0
	global_load_lds_dwordx4 v188, s[0:1]
	s_add_u32 s0, s56, 0x166000
	s_addc_u32 s1, s57, 0
	s_add_i32 s38, s25, 0xe000
	s_mov_b32 m0, s38
	s_nop 0
	global_load_lds_dwordx4 v188, s[0:1]
	s_waitcnt vmcnt(8)
	v_readlane_b32 s0, v255, 15
	s_mov_b32 s38, 0
	s_add_i32 s65, s25, 0xc000
	s_add_i32 s66, s25, 0xe000
	v_or_b32_e32 v234, s4, v2
	v_add_u32_e32 v236, 0, v0
	v_add_u32_e32 v237, 0, v3
	v_readlane_b32 s51, v255, 14
	s_mov_b32 s50, s0
	s_barrier
	v_readlane_b32 s1, v255, 16

; #define PG8_STAGE(bufoff, gbase, hoff, imm) do { _Pragma("unroll") for (int _i = 0; _i < 2; ++_i) { \
;         asm volatile("s_mov_b32 m0, %0\n\ts_nop 0\n\tglobal_load_lds_dwordx4 %1, %2" \
;             :: "s"(lds0 + (unsigned)((bufoff) + _i * 8192)), "v"(voff0), "s"((const char*)(gbase) + (size_t)(hoff) + (size_t)(_i * 8192)) : "memory"); } } while (0)
; #define PG8_LDA(dst, b, h) do { _Pragma("unroll") for (int m = 0; m < 4; ++m) _Pragma("unroll") for (int k = 0; k < 2; ++k) dst[m][k] = *(const LAS bf16x8*)(lds + PG8_SA(b, h) + aoff + m * 2048 + k * 1024); } while (0)
; #define PG8_LDB(dst, b, h) do { _Pragma("unroll") for (int n = 0; n < 2; ++n) _Pragma("unroll") for (int k = 0; k < 2; ++k) dst[n][k] = *(const LAS bf16x8*)(lds + PG8_SB(b, h) + boff + n * 2048 + k * 1024); } while (0)
; #define PG8_MMA(ai, bj, At, Bt) do { __builtin_amdgcn_s_setprio(1); _Pragma("unroll") for (int m = 0; m < 4; ++m) _Pragma("unroll") for (int n = 0; n < 2; ++n) _Pragma("unroll") for (int k = 0; k < 2; ++k) \
;         acc[ai][bj][m][n] = __builtin_amdgcn_mfma_f32_16x16x32_bf16(Bt[n][k], At[m][k], acc[ai][bj][m][n], 0, 0, 0); __builtin_amdgcn_s_setprio(0); } while (0)
; #define PG8_WAIT_L(n) asm volatile("s_waitcnt lgkmcnt(" #n ")" ::: "memory")
; #define PG8_BAR __builtin_amdgcn_s_barrier()
; #define PG8_SCHED __builtin_amdgcn_sched_barrier(0)
; template <class Epi>
; __device__ __forceinline__ void gemm_phase(LAS unsigned char* lds, const Gemm g, const StaticOrder& S, const Epi& E) {
;     ...
;             const char* aT = cA + (size_t)t * KS;
;             const char* a2 = last ? nA : aT + 2 * KS; const char* b2 = last ? nB : cB + (size_t)(t + 2) * KS;
;             PG8_LDB(B0, 0, 0); PG8_SCHED; PG8_LDA(At, 0, 0); PG8_STAGE(PG8_SA(1, 1), aT + KS, hA, 0);
;             PG8_WAIT_L(8); PG8_BAR; PG8_WAIT_L(0); PG8_MMA(0, 0, At, B0); PG8_BAR; PG8_SCHED;
;             PG8_LDB(B1, 0, 1); PG8_STAGE(PG8_SB(0, 0), b2, 0, 0);
;             PG8_BAR; PG8_WAIT_L(0); PG8_MMA(0, 1, At, B1); PG8_BAR;
;             PG8_LDA(At, 0, 1); PG8_STAGE(PG8_SA(0, 0), a2, 0, 0);
;             PG8_BAR; PG8_WAIT_L(0); PG8_MMA(1, 0, At, B0); PG8_BAR; PG8_SCHED;
.LBB0_860:
	s_add_u32 s58, s56, 0x8000
	v_add_u32_e32 v132, 0x10000, v236
	s_addc_u32 s59, s57, 0
	ds_read_b128 v[120:123], v132
	ds_read_b128 v[124:127], v132 offset:1024
	ds_read_b128 v[128:131], v132 offset:2048
	ds_read_b128 v[132:135], v132 offset:3072
	s_add_u32 s48, s56, 0x164000
	s_addc_u32 s49, s57, 0
	s_add_u32 s60, s56, 0x166000
	s_addc_u32 s61, s57, 0
	s_cmpk_eq_i32 s69, 0x54
	s_cselect_b32 s57, s7, s59
	s_cselect_b32 s56, s6, s58
	ds_read_b128 v[136:139], v237
	ds_read_b128 v[140:143], v237 offset:1024
	ds_read_b128 v[152:155], v237 offset:2048
	ds_read_b128 v[156:159], v237 offset:3072
	ds_read_b128 v[160:163], v237 offset:4096
	ds_read_b128 v[164:167], v237 offset:5120
	ds_read_b128 v[168:171], v237 offset:6144
	ds_read_b128 v[172:175], v237 offset:7168
	s_waitcnt lgkmcnt(8)
	s_waitcnt vmcnt(10)
	s_barrier
	s_waitcnt lgkmcnt(0)
	s_waitcnt lgkmcnt(7)
	v_mfma_f32_16x16x32_bf16 v[148:151], v[120:123], v[136:139], v[148:151]
	v_mfma_f32_16x16x32_bf16 v[144:147], v[128:131], v[136:139], v[144:147]
	s_waitcnt lgkmcnt(5)
	v_mfma_f32_16x16x32_bf16 v[108:111], v[120:123], v[152:155], v[108:111]
	v_mfma_f32_16x16x32_bf16 v[104:107], v[128:131], v[152:155], v[104:107]
	s_waitcnt lgkmcnt(3)
	v_mfma_f32_16x16x32_bf16 v[92:95], v[120:123], v[160:163], v[92:95]
	v_mfma_f32_16x16x32_bf16 v[88:91], v[128:131], v[160:163], v[88:91]
	s_waitcnt lgkmcnt(1)
	v_mfma_f32_16x16x32_bf16 v[76:79], v[120:123], v[168:171], v[76:79]
	v_mfma_f32_16x16x32_bf16 v[72:75], v[128:131], v[168:171], v[72:75]
	v_mfma_f32_16x16x32_bf16 v[148:151], v[124:127], v[140:143], v[148:151]
	v_mfma_f32_16x16x32_bf16 v[144:147], v[132:135], v[140:143], v[144:147]
	v_mfma_f32_16x16x32_bf16 v[108:111], v[124:127], v[156:159], v[108:111]
	v_mfma_f32_16x16x32_bf16 v[104:107], v[132:135], v[156:159], v[104:107]
	v_mfma_f32_16x16x32_bf16 v[92:95], v[124:127], v[164:167], v[92:95]
	v_mfma_f32_16x16x32_bf16 v[88:91], v[132:135], v[164:167], v[88:91]
	s_waitcnt lgkmcnt(0)
	v_mfma_f32_16x16x32_bf16 v[76:79], v[124:127], v[172:175], v[76:79]
	v_mfma_f32_16x16x32_bf16 v[72:75], v[132:135], v[172:175], v[72:75]
	s_barrier
	v_add_u32_e32 v200, 0x14000, v236
	ds_read_b128 v[176:179], v200
	ds_read_b128 v[180:183], v200 offset:1024
	ds_read_b128 v[184:187], v200 offset:2048
	ds_read_b128 v[200:203], v200 offset:3072
	s_cselect_b32 s60, s8, s0
	s_cselect_b32 s61, s9, s1
	s_mov_b32 m0, s26
	s_nop 0
	global_load_lds_dwordx4 v188, s[60:61]
	s_add_u32 s48, s60, 0x2000
	s_addc_u32 s49, s61, 0
	s_mov_b32 m0, s27
	s_nop 0
	global_load_lds_dwordx4 v188, s[48:49]
	s_waitcnt vmcnt(10)
	s_barrier
	s_waitcnt lgkmcnt(0)
	s_waitcnt lgkmcnt(3)
	v_mfma_f32_16x16x32_bf16 v[116:119], v[176:179], v[136:139], v[116:119]
	s_waitcnt lgkmcnt(1)
	v_mfma_f32_16x16x32_bf16 v[112:115], v[184:187], v[136:139], v[112:115]
	v_mfma_f32_16x16x32_bf16 v[100:103], v[176:179], v[152:155], v[100:103]
	v_mfma_f32_16x16x32_bf16 v[96:99], v[184:187], v[152:155], v[96:99]
	v_mfma_f32_16x16x32_bf16 v[84:87], v[176:179], v[160:163], v[84:87]
	v_mfma_f32_16x16x32_bf16 v[80:83], v[184:187], v[160:163], v[80:83]
	v_mfma_f32_16x16x32_bf16 v[68:71], v[176:179], v[168:171], v[68:71]
	v_mfma_f32_16x16x32_bf16 v[64:67], v[184:187], v[168:171], v[64:67]
	v_mfma_f32_16x16x32_bf16 v[116:119], v[180:183], v[140:143], v[116:119]
	s_waitcnt lgkmcnt(0)
	v_mfma_f32_16x16x32_bf16 v[112:115], v[200:203], v[140:143], v[112:115]
	v_mfma_f32_16x16x32_bf16 v[100:103], v[180:183], v[156:159], v[100:103]
	v_mfma_f32_16x16x32_bf16 v[96:99], v[200:203], v[156:159], v[96:99]
	v_mfma_f32_16x16x32_bf16 v[84:87], v[180:183], v[164:167], v[84:87]
	v_mfma_f32_16x16x32_bf16 v[80:83], v[200:203], v[164:167], v[80:83]
	v_mfma_f32_16x16x32_bf16 v[68:71], v[180:183], v[172:175], v[68:71]
	v_mfma_f32_16x16x32_bf16 v[64:67], v[200:203], v[172:175], v[64:67]
	s_barrier
	ds_read_b128 v[136:139], v237 offset:16384
	ds_read_b128 v[140:143], v237 offset:17408
	ds_read_b128 v[152:155], v237 offset:18432
	ds_read_b128 v[156:159], v237 offset:19456
	ds_read_b128 v[160:163], v237 offset:20480
	ds_read_b128 v[164:167], v237 offset:21504
	ds_read_b128 v[168:171], v237 offset:22528
	ds_read_b128 v[172:175], v237 offset:23552
	s_mov_b32 m0, s25
	s_nop 0
	global_load_lds_dwordx4 v188, s[56:57]
	s_add_u32 s48, s56, 0x2000
	s_addc_u32 s49, s57, 0
	s_mov_b32 m0, s28
	s_nop 0
	global_load_lds_dwordx4 v188, s[48:49]
	s_barrier
	s_waitcnt lgkmcnt(0)
	s_waitcnt lgkmcnt(7)
	v_mfma_f32_16x16x32_bf16 v[60:63], v[120:123], v[136:139], v[60:63]
	v_mfma_f32_16x16x32_bf16 v[56:59], v[128:131], v[136:139], v[56:59]
	s_waitcnt lgkmcnt(5)
	v_mfma_f32_16x16x32_bf16 v[44:47], v[120:123], v[152:155], v[44:47]
	v_mfma_f32_16x16x32_bf16 v[40:43], v[128:131], v[152:155], v[40:43]
	s_waitcnt lgkmcnt(3)
	v_mfma_f32_16x16x32_bf16 v[28:31], v[120:123], v[160:163], v[28:31]
	v_mfma_f32_16x16x32_bf16 v[24:27], v[128:131], v[160:163], v[24:27]
	s_waitcnt lgkmcnt(1)
	v_mfma_f32_16x16x32_bf16 v[12:15], v[120:123], v[168:171], v[12:15]
	v_mfma_f32_16x16x32_bf16 v[8:11], v[128:131], v[168:171], v[8:11]
	v_mfma_f32_16x16x32_bf16 v[60:63], v[124:127], v[140:143], v[60:63]
	v_mfma_f32_16x16x32_bf16 v[56:59], v[132:135], v[140:143], v[56:59]
	v_mfma_f32_16x16x32_bf16 v[44:47], v[124:127], v[156:159], v[44:47]
	v_mfma_f32_16x16x32_bf16 v[40:43], v[132:135], v[156:159], v[40:43]
	v_mfma_f32_16x16x32_bf16 v[28:31], v[124:127], v[164:167], v[28:31]
	v_mfma_f32_16x16x32_bf16 v[24:27], v[132:135], v[164:167], v[24:27]
	s_waitcnt lgkmcnt(0)
	v_mfma_f32_16x16x32_bf16 v[12:15], v[124:127], v[172:175], v[12:15]
	v_mfma_f32_16x16x32_bf16 v[8:11], v[132:135], v[172:175], v[8:11]
	s_barrier
; #define PG8_STAGE(bufoff, gbase, hoff, imm) do { _Pragma("unroll") for (int _i = 0; _i < 2; ++_i) { \
;         asm volatile("s_mov_b32 m0, %0\n\ts_nop 0\n\tglobal_load_lds_dwordx4 %1, %2" \
;             :: "s"(lds0 + (unsigned)((bufoff) + _i * 8192)), "v"(voff0), "s"((const char*)(gbase) + (size_t)(hoff) + (size_t)(_i * 8192)) : "memory"); } } while (0)
; #define PG8_LDA(dst, b, h) do { _Pragma("unroll") for (int m = 0; m < 4; ++m) _Pragma("unroll") for (int k = 0; k < 2; ++k) dst[m][k] = *(const LAS bf16x8*)(lds + PG8_SA(b, h) + aoff + m * 2048 + k * 1024); } while (0)
; #define PG8_LDB(dst, b, h) do { _Pragma("unroll") for (int n = 0; n < 2; ++n) _Pragma("unroll") for (int k = 0; k < 2; ++k) dst[n][k] = *(const LAS bf16x8*)(lds + PG8_SB(b, h) + boff + n * 2048 + k * 1024); } while (0)
; #define PG8_MMA(ai, bj, At, Bt) do { __builtin_amdgcn_s_setprio(1); _Pragma("unroll") for (int m = 0; m < 4; ++m) _Pragma("unroll") for (int n = 0; n < 2; ++n) _Pragma("unroll") for (int k = 0; k < 2; ++k) \
;         acc[ai][bj][m][n] = __builtin_amdgcn_mfma_f32_16x16x32_bf16(Bt[n][k], At[m][k], acc[ai][bj][m][n], 0, 0, 0); __builtin_amdgcn_s_setprio(0); } while (0)
; #define PG8_WAIT_V(n) asm volatile("s_waitcnt vmcnt(" #n ")" ::: "memory")
; #define PG8_WAIT_L(n) asm volatile("s_waitcnt lgkmcnt(" #n ")" ::: "memory")
; #define PG8_BAR __builtin_amdgcn_s_barrier()
; #define PG8_SCHED __builtin_amdgcn_sched_barrier(0)
; template <class Epi>
; __device__ __forceinline__ void gemm_phase(LAS unsigned char* lds, const Gemm g, const StaticOrder& S, const Epi& E) {
;     ...
;             PG8_STAGE(PG8_SB(0, 1), b2, hB, 0);
;             PG8_WAIT_V(6); PG8_BAR; PG8_MMA(1, 1, At, B1); PG8_BAR;
;             PG8_LDB(B0, 1, 0); PG8_SCHED; PG8_LDA(At, 1, 0); PG8_STAGE(PG8_SA(0, 1), a2, hA, 0);
;             PG8_WAIT_L(8); PG8_BAR; PG8_WAIT_L(0); PG8_MMA(0, 0, At, B0); PG8_BAR; PG8_SCHED;
;             PG8_LDB(B1, 1, 1); PG8_STAGE(PG8_SB(1, 0), b2 + KS, 0, 0);
;             PG8_BAR; PG8_WAIT_L(0); PG8_MMA(0, 1, At, B1); PG8_BAR;
;             PG8_LDA(At, 1, 1); PG8_STAGE(PG8_SA(1, 0), a2 + KS, 0, 0);
	s_add_u32 s48, s60, 0x160000
	s_addc_u32 s49, s61, 0
	s_mov_b32 m0, s29
	s_nop 0
	global_load_lds_dwordx4 v188, s[48:49]
	s_add_u32 s48, s60, 0x162000
	s_addc_u32 s49, s61, 0
	s_mov_b32 m0, s30
	s_nop 0
	global_load_lds_dwordx4 v188, s[48:49]
	s_add_u32 s48, s56, 0x160000
	s_addc_u32 s49, s57, 0
	s_mov_b32 m0, s34
	s_nop 0
	global_load_lds_dwordx4 v188, s[48:49]
	s_add_u32 s48, s56, 0x162000
	s_addc_u32 s49, s57, 0
	s_mov_b32 m0, s37
	s_nop 0
	global_load_lds_dwordx4 v188, s[48:49]
	s_waitcnt vmcnt(12)
	s_barrier
	v_mfma_f32_16x16x32_bf16 v[52:55], v[176:179], v[136:139], v[52:55]
	v_mfma_f32_16x16x32_bf16 v[48:51], v[184:187], v[136:139], v[48:51]
	v_mfma_f32_16x16x32_bf16 v[36:39], v[176:179], v[152:155], v[36:39]
	v_mfma_f32_16x16x32_bf16 v[32:35], v[184:187], v[152:155], v[32:35]
	v_mfma_f32_16x16x32_bf16 v[20:23], v[176:179], v[160:163], v[20:23]
	v_mfma_f32_16x16x32_bf16 v[16:19], v[184:187], v[160:163], v[16:19]
	v_mfma_f32_16x16x32_bf16 v[4:7], v[176:179], v[168:171], v[4:7]
	v_mfma_f32_16x16x32_bf16 v[0:3], v[184:187], v[168:171], v[0:3]
	v_mfma_f32_16x16x32_bf16 v[52:55], v[180:183], v[140:143], v[52:55]
	v_mfma_f32_16x16x32_bf16 v[48:51], v[200:203], v[140:143], v[48:51]
	v_mfma_f32_16x16x32_bf16 v[36:39], v[180:183], v[156:159], v[36:39]
	v_mfma_f32_16x16x32_bf16 v[32:35], v[200:203], v[156:159], v[32:35]
	v_mfma_f32_16x16x32_bf16 v[20:23], v[180:183], v[164:167], v[20:23]
	v_mfma_f32_16x16x32_bf16 v[16:19], v[200:203], v[164:167], v[16:19]
	v_mfma_f32_16x16x32_bf16 v[4:7], v[180:183], v[172:175], v[4:7]
	v_mfma_f32_16x16x32_bf16 v[0:3], v[200:203], v[172:175], v[0:3]
	v_add_u32_e32 v132, 0x18000, v236
	s_barrier
	ds_read_b128 v[120:123], v132
	ds_read_b128 v[124:127], v132 offset:1024
	ds_read_b128 v[128:131], v132 offset:2048
	ds_read_b128 v[132:135], v132 offset:3072
	ds_read_b128 v[136:139], v237 offset:32768
	ds_read_b128 v[140:143], v237 offset:33792
	ds_read_b128 v[152:155], v237 offset:34816
	ds_read_b128 v[156:159], v237 offset:35840
	ds_read_b128 v[160:163], v237 offset:36864
	ds_read_b128 v[164:167], v237 offset:37888
	ds_read_b128 v[168:171], v237 offset:38912
	ds_read_b128 v[172:175], v237 offset:39936
	s_waitcnt lgkmcnt(8)
	s_waitcnt vmcnt(10)
	s_barrier
	s_waitcnt lgkmcnt(0)
	s_waitcnt lgkmcnt(7)
	v_mfma_f32_16x16x32_bf16 v[148:151], v[120:123], v[136:139], v[148:151]
	v_mfma_f32_16x16x32_bf16 v[144:147], v[128:131], v[136:139], v[144:147]
	s_waitcnt lgkmcnt(5)
	v_mfma_f32_16x16x32_bf16 v[108:111], v[120:123], v[152:155], v[108:111]
	v_mfma_f32_16x16x32_bf16 v[104:107], v[128:131], v[152:155], v[104:107]
	s_waitcnt lgkmcnt(3)
	v_mfma_f32_16x16x32_bf16 v[92:95], v[120:123], v[160:163], v[92:95]
	v_mfma_f32_16x16x32_bf16 v[88:91], v[128:131], v[160:163], v[88:91]
	s_waitcnt lgkmcnt(1)
	v_mfma_f32_16x16x32_bf16 v[76:79], v[120:123], v[168:171], v[76:79]
	v_mfma_f32_16x16x32_bf16 v[72:75], v[128:131], v[168:171], v[72:75]
	v_mfma_f32_16x16x32_bf16 v[148:151], v[124:127], v[140:143], v[148:151]
	v_mfma_f32_16x16x32_bf16 v[144:147], v[132:135], v[140:143], v[144:147]
	v_mfma_f32_16x16x32_bf16 v[108:111], v[124:127], v[156:159], v[108:111]
	v_mfma_f32_16x16x32_bf16 v[104:107], v[132:135], v[156:159], v[104:107]
	v_mfma_f32_16x16x32_bf16 v[92:95], v[124:127], v[164:167], v[92:95]
	v_mfma_f32_16x16x32_bf16 v[88:91], v[132:135], v[164:167], v[88:91]
	s_waitcnt lgkmcnt(0)
	v_mfma_f32_16x16x32_bf16 v[76:79], v[124:127], v[172:175], v[76:79]
	v_mfma_f32_16x16x32_bf16 v[72:75], v[132:135], v[172:175], v[72:75]
	s_barrier
	v_add_u32_e32 v200, 0x1c000, v236
	ds_read_b128 v[176:179], v200
	ds_read_b128 v[180:183], v200 offset:1024
	ds_read_b128 v[184:187], v200 offset:2048
	ds_read_b128 v[200:203], v200 offset:3072
	s_add_u32 s48, s60, 0x4000
	s_addc_u32 s49, s61, 0
	s_mov_b32 m0, s41
	s_nop 0
	global_load_lds_dwordx4 v188, s[48:49]
	s_add_u32 s48, s60, 0x6000
	s_addc_u32 s49, s61, 0
	s_mov_b32 m0, s42
	s_nop 0
	global_load_lds_dwordx4 v188, s[48:49]
	s_waitcnt vmcnt(10)
	s_barrier
	s_waitcnt lgkmcnt(0)
	s_waitcnt lgkmcnt(3)
	v_mfma_f32_16x16x32_bf16 v[116:119], v[176:179], v[136:139], v[116:119]
	s_waitcnt lgkmcnt(1)
	v_mfma_f32_16x16x32_bf16 v[112:115], v[184:187], v[136:139], v[112:115]
	v_mfma_f32_16x16x32_bf16 v[100:103], v[176:179], v[152:155], v[100:103]
	v_mfma_f32_16x16x32_bf16 v[96:99], v[184:187], v[152:155], v[96:99]
	v_mfma_f32_16x16x32_bf16 v[84:87], v[176:179], v[160:163], v[84:87]
	v_mfma_f32_16x16x32_bf16 v[80:83], v[184:187], v[160:163], v[80:83]
	v_mfma_f32_16x16x32_bf16 v[68:71], v[176:179], v[168:171], v[68:71]
	v_mfma_f32_16x16x32_bf16 v[64:67], v[184:187], v[168:171], v[64:67]
	v_mfma_f32_16x16x32_bf16 v[116:119], v[180:183], v[140:143], v[116:119]
	s_waitcnt lgkmcnt(0)
	v_mfma_f32_16x16x32_bf16 v[112:115], v[200:203], v[140:143], v[112:115]
	v_mfma_f32_16x16x32_bf16 v[100:103], v[180:183], v[156:159], v[100:103]
	v_mfma_f32_16x16x32_bf16 v[96:99], v[200:203], v[156:159], v[96:99]
	v_mfma_f32_16x16x32_bf16 v[84:87], v[180:183], v[164:167], v[84:87]
	v_mfma_f32_16x16x32_bf16 v[80:83], v[200:203], v[164:167], v[80:83]
	v_mfma_f32_16x16x32_bf16 v[68:71], v[180:183], v[172:175], v[68:71]
	v_mfma_f32_16x16x32_bf16 v[64:67], v[200:203], v[172:175], v[64:67]
	s_barrier
	ds_read_b128 v[136:139], v237 offset:49152
	ds_read_b128 v[140:143], v237 offset:50176
	ds_read_b128 v[152:155], v237 offset:51200
	ds_read_b128 v[156:159], v237 offset:52224
	ds_read_b128 v[160:163], v237 offset:53248
	ds_read_b128 v[164:167], v237 offset:54272
	ds_read_b128 v[168:171], v237 offset:55296
	ds_read_b128 v[172:175], v237 offset:56320
	s_add_u32 s48, s56, 0x4000
	s_addc_u32 s49, s57, 0
	s_mov_b32 m0, s43
	s_nop 0
	global_load_lds_dwordx4 v188, s[48:49]
	s_add_u32 s48, s56, 0x6000
	s_addc_u32 s49, s57, 0
	s_mov_b32 m0, s62
	s_nop 0
	global_load_lds_dwordx4 v188, s[48:49]
	s_barrier
; template <class Epi>
; __device__ __forceinline__ void gemm_phase(LAS unsigned char* lds, const Gemm g, const StaticOrder& S, const Epi& E) {
;     ...
;             PG8_BAR; PG8_WAIT_L(0); PG8_MMA(1, 0, At, B0); PG8_BAR; PG8_SCHED;
;             PG8_STAGE(PG8_SB(1, 1), b2 + KS, hB, 0);
;             PG8_WAIT_V(6); PG8_BAR; PG8_MMA(1, 1, At, B1); PG8_BAR;
;         }
;     __device__ __forceinline__ void operator()(f32x4 (&acc)[2][2][4][2], const Unit& u, int wr, int wc, int fr, int fq, LAS unsigned char*) const {
;         const int b = u.pm >> 6;
;         const int col0 = u.pn * BM + wc * 32 + 8 * fq;
;         const size_t off0 = (size_t)(u.pm * BM + wr * 64 + fr) * D + col0;
;         f32x4 sc[2][2];
; #pragma unroll
;         for (int bj = 0; bj < 2; ++bj)
; #pragma unroll
;             for (int n = 0; n < 2; ++n) { f32x4 gt = *(const f32x4*)(gate + (size_t)b * MODW + col0 + bj * HALF + n * 4); sc[bj][n] = gt + 1.0f;
;                 if (cs) sc[bj][n] *= *(const f32x4*)(cs + col0 + bj * HALF + n * 4); }
;         if (IN_F32) {
; #pragma unroll
;             for (int ai = 0; ai < 2; ++ai) {
;                 f32x4 r[4][2][2];
; #pragma unroll
;                 for (int m = 0; m < 4; ++m)
; #pragma unroll
;                     for (int bj = 0; bj < 2; ++bj)
; #pragma unroll
;                         for (int n = 0; n < 2; ++n) r[m][bj][n] = *(const f32x4*)((const float*)in + off0 + (size_t)(ai * HALF + m * 16) * D + bj * HALF + n * 4);
; #pragma unroll
;                 for (int m = 0; m < 4; ++m)
; #pragma unroll
;                     for (int bj = 0; bj < 2; ++bj) { const f32x4 r0 = r[m][bj][0] + sc[bj][0] * acc[ai][bj][m][0], r1 = r[m][bj][1] + sc[bj][1] * acc[ai][bj][m][1];
;                         u32x4 w; w.x = cvt_pk_bf16(r0[0], r0[1]); w.y = cvt_pk_bf16(r0[2], r0[3]); w.z = cvt_pk_bf16(r1[0], r1[1]); w.w = cvt_pk_bf16(r1[2], r1[3]);
;                         *(u32x4*)(out + off0 + (size_t)(ai * HALF + m * 16) * D + bj * HALF) = w; }
;                 asm volatile("" ::: "memory");
;             }
;         } else {
;             u32x4 xb[2][4][2];
; #pragma unroll
;             for (int ai = 0; ai < 2; ++ai)
; #pragma unroll
;                 for (int m = 0; m < 4; ++m)
; #pragma unroll
;                     for (int bj = 0; bj < 2; ++bj) xb[ai][m][bj] = *(const u32x4*)((const bf16_t*)in + off0 + (size_t)(ai * HALF + m * 16) * D + bj * HALF);
	s_waitcnt lgkmcnt(0)
	s_waitcnt lgkmcnt(7)
	v_mfma_f32_16x16x32_bf16 v[60:63], v[120:123], v[136:139], v[60:63]
	v_mfma_f32_16x16x32_bf16 v[56:59], v[128:131], v[136:139], v[56:59]
	s_waitcnt lgkmcnt(5)
	v_mfma_f32_16x16x32_bf16 v[44:47], v[120:123], v[152:155], v[44:47]
	v_mfma_f32_16x16x32_bf16 v[40:43], v[128:131], v[152:155], v[40:43]
	s_waitcnt lgkmcnt(3)
	v_mfma_f32_16x16x32_bf16 v[28:31], v[120:123], v[160:163], v[28:31]
	v_mfma_f32_16x16x32_bf16 v[24:27], v[128:131], v[160:163], v[24:27]
	s_waitcnt lgkmcnt(1)
	v_mfma_f32_16x16x32_bf16 v[12:15], v[120:123], v[168:171], v[12:15]
	v_mfma_f32_16x16x32_bf16 v[8:11], v[128:131], v[168:171], v[8:11]
	v_mfma_f32_16x16x32_bf16 v[60:63], v[124:127], v[140:143], v[60:63]
	v_mfma_f32_16x16x32_bf16 v[56:59], v[132:135], v[140:143], v[56:59]
	v_mfma_f32_16x16x32_bf16 v[44:47], v[124:127], v[156:159], v[44:47]
	v_mfma_f32_16x16x32_bf16 v[40:43], v[132:135], v[156:159], v[40:43]
	v_mfma_f32_16x16x32_bf16 v[28:31], v[124:127], v[164:167], v[28:31]
	v_mfma_f32_16x16x32_bf16 v[24:27], v[132:135], v[164:167], v[24:27]
	s_waitcnt lgkmcnt(0)
	v_mfma_f32_16x16x32_bf16 v[12:15], v[124:127], v[172:175], v[12:15]
	v_mfma_f32_16x16x32_bf16 v[8:11], v[132:135], v[172:175], v[8:11]
	s_barrier
	s_add_u32 s48, s60, 0x164000
	s_addc_u32 s49, s61, 0
	s_mov_b32 m0, s63
	s_nop 0
	global_load_lds_dwordx4 v188, s[48:49]
	s_add_u32 s48, s60, 0x166000
	s_addc_u32 s49, s61, 0
	s_mov_b32 m0, s64
	s_nop 0
	global_load_lds_dwordx4 v188, s[48:49]
	s_add_u32 s48, s56, 0x164000
	s_addc_u32 s49, s57, 0
	s_mov_b32 m0, s65
	s_nop 0
	global_load_lds_dwordx4 v188, s[48:49]
	s_add_u32 s48, s56, 0x166000
	s_addc_u32 s49, s57, 0
	s_mov_b32 m0, s66
	s_nop 0
	global_load_lds_dwordx4 v188, s[48:49]
	s_waitcnt vmcnt(12)
	s_barrier
	v_mfma_f32_16x16x32_bf16 v[52:55], v[176:179], v[136:139], v[52:55]
	v_mfma_f32_16x16x32_bf16 v[48:51], v[184:187], v[136:139], v[48:51]
	v_mfma_f32_16x16x32_bf16 v[36:39], v[176:179], v[152:155], v[36:39]
	v_mfma_f32_16x16x32_bf16 v[32:35], v[184:187], v[152:155], v[32:35]
	v_mfma_f32_16x16x32_bf16 v[20:23], v[176:179], v[160:163], v[20:23]
	v_mfma_f32_16x16x32_bf16 v[16:19], v[184:187], v[160:163], v[16:19]
	v_mfma_f32_16x16x32_bf16 v[4:7], v[176:179], v[168:171], v[4:7]
	v_mfma_f32_16x16x32_bf16 v[0:3], v[184:187], v[168:171], v[0:3]
	v_mfma_f32_16x16x32_bf16 v[52:55], v[180:183], v[140:143], v[52:55]
	v_mfma_f32_16x16x32_bf16 v[48:51], v[200:203], v[140:143], v[48:51]
	v_mfma_f32_16x16x32_bf16 v[36:39], v[180:183], v[156:159], v[36:39]
	v_mfma_f32_16x16x32_bf16 v[32:35], v[200:203], v[156:159], v[32:35]
	v_mfma_f32_16x16x32_bf16 v[20:23], v[180:183], v[164:167], v[20:23]
	v_mfma_f32_16x16x32_bf16 v[16:19], v[200:203], v[164:167], v[16:19]
	v_mfma_f32_16x16x32_bf16 v[4:7], v[180:183], v[172:175], v[4:7]
	v_mfma_f32_16x16x32_bf16 v[0:3], v[200:203], v[172:175], v[0:3]
	s_add_i32 s69, s69, 2
	s_add_u32 s0, s0, 0x8000
	s_addc_u32 s1, s1, 0
	s_cmpk_gt_u32 s69, 0x55
	s_mov_b64 s[56:57], s[58:59]
	s_barrier
	s_cbranch_scc0 .LBB0_860
	s_ashr_i32 s0, s50, 6
	s_mul_hi_i32 s1, s0, 0xc000
	s_mul_i32 s0, s0, 0xc000
	v_lshl_or_b32 v128, s51, 8, v234
	s_add_u32 s0, s39, s0
	v_ashrrev_i32_e32 v129, 31, v128
	s_addc_u32 s1, s40, s1
	v_lshl_add_u64 v[130:131], v[128:129], 2, s[0:1]
	global_load_dwordx4 v[120:123], v[130:131], off offset:16
	global_load_dwordx4 v[124:127], v[130:131], off
	s_mov_b32 s51, s67
	s_mov_b64 s[58:59], s[8:9]
	s_mov_b64 s[56:57], s[6:7]
	s_waitcnt vmcnt(1)
	v_pk_add_f32 v[210:211], v[122:123], 1.0 op_sel_hi:[1,0]
	s_waitcnt vmcnt(0)
	v_pk_add_f32 v[214:215], v[126:127], 1.0 op_sel_hi:[1,0]
	v_pk_add_f32 v[212:213], v[124:125], 1.0 op_sel_hi:[1,0]
	v_pk_add_f32 v[208:209], v[120:121], 1.0 op_sel_hi:[1,0]
	global_load_dwordx4 v[120:123], v[130:131], off offset:528
	global_load_dwordx4 v[124:127], v[130:131], off offset:512
	s_waitcnt vmcnt(1)
	v_pk_add_f32 v[200:201], v[120:121], 1.0 op_sel_hi:[1,0]
	v_lshl_add_u32 v120, s50, 8, v233
	v_ashrrev_i32_e32 v121, 31, v120
	v_lshlrev_b64 v[120:121], 11, v[120:121]
	v_lshl_add_u64 v[120:121], v[120:121], 0, v[128:129]
	v_lshlrev_b64 v[216:217], 1, v[120:121]
	v_lshl_add_u64 v[120:121], s[52:53], 0, v[216:217]
	global_load_dwordx4 v[238:241], v[120:121], off
	global_load_dwordx4 v[184:187], v[120:121], off offset:256
	v_pk_add_f32 v[202:203], v[122:123], 1.0 op_sel_hi:[1,0]
	v_add_co_u32_e32 v122, vcc, s45, v120
	s_waitcnt vmcnt(2)
	v_pk_add_f32 v[206:207], v[126:127], 1.0 op_sel_hi:[1,0]
	v_addc_co_u32_e32 v123, vcc, 0, v121, vcc
	global_load_dwordx4 v[180:183], v[122:123], off
	global_load_dwordx4 v[176:179], v[122:123], off offset:256
	v_add_co_u32_e32 v122, vcc, s36, v120
	v_pk_add_f32 v[204:205], v[124:125], 1.0 op_sel_hi:[1,0]
	s_nop 0
	v_addc_co_u32_e32 v123, vcc, 0, v121, vcc
	global_load_dwordx4 v[172:175], v[122:123], off
	global_load_dwordx4 v[168:171], v[122:123], off offset:256
	v_add_co_u32_e32 v122, vcc, s23, v120
	s_mov_b32 s50, s68
	s_nop 0
	v_addc_co_u32_e32 v123, vcc, 0, v121, vcc
	global_load_dwordx4 v[164:167], v[122:123], off
	global_load_dwordx4 v[160:163], v[122:123], off offset:256
	v_add_co_u32_e32 v122, vcc, s93, v120
	s_waitcnt vmcnt(7)
; __device__ __forceinline__ unsigned cvt_pk_bf16(float lo, float hi) { unsigned r; asm volatile("v_cvt_pk_bf16_f32 %0, %1, %2" : "=v"(r) : "v"(lo), "v"(hi)); return r; }
;     __device__ __forceinline__ void operator()(f32x4 (&acc)[2][2][4][2], const Unit& u, int wr, int wc, int fr, int fq, LAS unsigned char*) const {
;     ...
;             u32x4 xb[2][4][2];
; #pragma unroll
;             for (int ai = 0; ai < 2; ++ai)
; #pragma unroll
;                 for (int m = 0; m < 4; ++m)
; #pragma unroll
;                     for (int bj = 0; bj < 2; ++bj) xb[ai][m][bj] = *(const u32x4*)((const bf16_t*)in + off0 + (size_t)(ai * HALF + m * 16) * D + bj * HALF);
; #pragma unroll
;             for (int ai = 0; ai < 2; ++ai)
; #pragma unroll
;                 for (int m = 0; m < 4; ++m)
; #pragma unroll
;                     for (int bj = 0; bj < 2; ++bj) { const u32x4 x = xb[ai][m][bj];
;                         f32x4 r0 = (f32x4){__uint_as_float(x.x << 16), __uint_as_float(x.x & 0xffff0000u), __uint_as_float(x.y << 16), __uint_as_float(x.y & 0xffff0000u)};
;                         f32x4 r1 = (f32x4){__uint_as_float(x.z << 16), __uint_as_float(x.z & 0xffff0000u), __uint_as_float(x.w << 16), __uint_as_float(x.w & 0xffff0000u)};
;                         r0 += sc[bj][0] * acc[ai][bj][m][0]; r1 += sc[bj][1] * acc[ai][bj][m][1];
;                         u32x4 w; w.x = cvt_pk_bf16(r0[0], r0[1]); w.y = cvt_pk_bf16(r0[2], r0[3]); w.z = cvt_pk_bf16(r1[0], r1[1]); w.w = cvt_pk_bf16(r1[2], r1[3]);
;                         *(u32x4*)(out + off0 + (size_t)(ai * HALF + m * 16) * D + bj * HALF) = w; }
	v_lshlrev_b32_e32 v230, 16, v238
	v_addc_co_u32_e32 v123, vcc, 0, v121, vcc
	global_load_dwordx4 v[156:159], v[122:123], off
	global_load_dwordx4 v[152:155], v[122:123], off offset:256
	v_add_co_u32_e32 v122, vcc, s33, v120
	v_and_b32_e32 v231, 0xffff0000, v238
	s_nop 0
	v_addc_co_u32_e32 v123, vcc, 0, v121, vcc
	global_load_dwordx4 v[140:143], v[122:123], off
	global_load_dwordx4 v[136:139], v[122:123], off offset:256
	v_add_co_u32_e32 v122, vcc, s18, v120
	v_lshlrev_b32_e32 v242, 16, v240
	s_nop 0
	v_addc_co_u32_e32 v123, vcc, 0, v121, vcc
	global_load_dwordx4 v[132:135], v[122:123], off
	global_load_dwordx4 v[128:131], v[122:123], off offset:256
	v_add_co_u32_e32 v120, vcc, s19, v120
	v_and_b32_e32 v243, 0xffff0000, v240
	s_nop 0
	v_addc_co_u32_e32 v121, vcc, 0, v121, vcc
	global_load_dwordx4 v[124:127], v[120:121], off
	s_nop 0
	global_load_dwordx4 v[120:123], v[120:121], off offset:256
	v_lshlrev_b32_e32 v238, 16, v239
	v_and_b32_e32 v239, 0xffff0000, v239
	v_lshlrev_b32_e32 v240, 16, v241
	v_and_b32_e32 v241, 0xffff0000, v241
	v_pk_fma_f32 v[148:149], v[148:149], v[212:213], v[230:231]
	v_pk_fma_f32 v[144:145], v[144:145], v[208:209], v[242:243]
	v_pk_fma_f32 v[150:151], v[150:151], v[214:215], v[238:239]
	v_pk_fma_f32 v[230:231], v[146:147], v[210:211], v[240:241]
	v_cvt_pk_bf16_f32 v146, v148, v149
	v_cvt_pk_bf16_f32 v147, v150, v151
	v_cvt_pk_bf16_f32 v148, v144, v145
	v_lshl_add_u64 v[144:145], s[54:55], 0, v[216:217]
	v_cvt_pk_bf16_f32 v149, v230, v231
	global_store_dwordx4 v[144:145], v[146:149], off
	s_waitcnt vmcnt(15)
	v_lshlrev_b32_e32 v150, 16, v186
	v_and_b32_e32 v151, 0xffff0000, v186
	v_lshlrev_b32_e32 v146, 16, v184
	v_and_b32_e32 v147, 0xffff0000, v184
	v_lshlrev_b32_e32 v148, 16, v185
	v_and_b32_e32 v149, 0xffff0000, v185
	v_lshlrev_b32_e32 v184, 16, v187
	v_and_b32_e32 v185, 0xffff0000, v187
	v_pk_fma_f32 v[118:119], v[118:119], v[206:207], v[148:149]
	v_pk_fma_f32 v[116:117], v[116:117], v[204:205], v[146:147]
	v_pk_fma_f32 v[146:147], v[114:115], v[202:203], v[184:185]
	v_pk_fma_f32 v[114:115], v[112:113], v[200:201], v[150:151]
	v_cvt_pk_bf16_f32 v112, v116, v117
	v_cvt_pk_bf16_f32 v113, v118, v119
	s_waitcnt vmcnt(14)
	v_lshlrev_b32_e32 v116, 16, v182
	v_cvt_pk_bf16_f32 v114, v114, v115
	v_cvt_pk_bf16_f32 v115, v146, v147
	global_store_dwordx4 v[144:145], v[112:115], off offset:256
	v_and_b32_e32 v117, 0xffff0000, v182
	v_lshlrev_b32_e32 v118, 16, v183
	v_lshlrev_b32_e32 v112, 16, v180
	v_and_b32_e32 v113, 0xffff0000, v180
	v_and_b32_e32 v119, 0xffff0000, v183
	v_pk_fma_f32 v[108:109], v[108:109], v[212:213], v[112:113]
	v_lshlrev_b32_e32 v114, 16, v181
	v_and_b32_e32 v115, 0xffff0000, v181
	v_pk_fma_f32 v[112:113], v[106:107], v[210:211], v[118:119]
	v_pk_fma_f32 v[106:107], v[104:105], v[208:209], v[116:117]
	v_cvt_pk_bf16_f32 v104, v108, v109
	v_add_co_u32_e32 v108, vcc, s45, v144
	v_pk_fma_f32 v[110:111], v[110:111], v[214:215], v[114:115]
	s_nop 0
	v_addc_co_u32_e32 v109, vcc, 0, v145, vcc
	v_cvt_pk_bf16_f32 v105, v110, v111
	v_cvt_pk_bf16_f32 v106, v106, v107
	v_cvt_pk_bf16_f32 v107, v112, v113
	global_store_dwordx4 v[108:109], v[104:107], off
	s_waitcnt vmcnt(15)
	v_lshlrev_b32_e32 v110, 16, v178
	v_and_b32_e32 v111, 0xffff0000, v178
	v_lshlrev_b32_e32 v104, 16, v176
	v_and_b32_e32 v105, 0xffff0000, v176
	v_lshlrev_b32_e32 v106, 16, v177
	v_and_b32_e32 v107, 0xffff0000, v177
	v_lshlrev_b32_e32 v112, 16, v179
	v_and_b32_e32 v113, 0xffff0000, v179
	v_pk_fma_f32 v[102:103], v[102:103], v[206:207], v[106:107]
	v_pk_fma_f32 v[100:101], v[100:101], v[204:205], v[104:105]
	v_pk_fma_f32 v[104:105], v[98:99], v[202:203], v[112:113]
	v_pk_fma_f32 v[98:99], v[96:97], v[200:201], v[110:111]
	v_cvt_pk_bf16_f32 v96, v100, v101
	v_cvt_pk_bf16_f32 v97, v102, v103
	s_waitcnt vmcnt(14)
	v_lshlrev_b32_e32 v100, 16, v174
	v_cvt_pk_bf16_f32 v98, v98, v99
	v_cvt_pk_bf16_f32 v99, v104, v105
	global_store_dwordx4 v[108:109], v[96:99], off offset:256
	v_and_b32_e32 v101, 0xffff0000, v174
	v_lshlrev_b32_e32 v102, 16, v175
	v_lshlrev_b32_e32 v96, 16, v172
	v_and_b32_e32 v97, 0xffff0000, v172
	v_and_b32_e32 v103, 0xffff0000, v175
	v_pk_fma_f32 v[92:93], v[92:93], v[212:213], v[96:97]
	v_lshlrev_b32_e32 v98, 16, v173
	v_and_b32_e32 v99, 0xffff0000, v173
	v_pk_fma_f32 v[96:97], v[90:91], v[210:211], v[102:103]
	v_pk_fma_f32 v[90:91], v[88:89], v[208:209], v[100:101]
	v_cvt_pk_bf16_f32 v88, v92, v93
	v_add_co_u32_e32 v92, vcc, s36, v144
	v_pk_fma_f32 v[94:95], v[94:95], v[214:215], v[98:99]
	s_nop 0
	v_addc_co_u32_e32 v93, vcc, 0, v145, vcc
	v_cvt_pk_bf16_f32 v89, v94, v95
	v_cvt_pk_bf16_f32 v90, v90, v91
	v_cvt_pk_bf16_f32 v91, v96, v97
	global_store_dwordx4 v[92:93], v[88:91], off
	s_waitcnt vmcnt(15)
	v_lshlrev_b32_e32 v94, 16, v170
	v_and_b32_e32 v95, 0xffff0000, v170
	v_lshlrev_b32_e32 v88, 16, v168
	v_and_b32_e32 v89, 0xffff0000, v168
	v_lshlrev_b32_e32 v90, 16, v169
	v_and_b32_e32 v91, 0xffff0000, v169
	v_lshlrev_b32_e32 v96, 16, v171
	v_and_b32_e32 v97, 0xffff0000, v171
	v_pk_fma_f32 v[86:87], v[86:87], v[206:207], v[90:91]
	v_pk_fma_f32 v[84:85], v[84:85], v[204:205], v[88:89]
	v_pk_fma_f32 v[88:89], v[82:83], v[202:203], v[96:97]
	v_pk_fma_f32 v[82:83], v[80:81], v[200:201], v[94:95]
	v_cvt_pk_bf16_f32 v80, v84, v85
	v_cvt_pk_bf16_f32 v81, v86, v87
	s_waitcnt vmcnt(14)
; __device__ __forceinline__ unsigned cvt_pk_bf16(float lo, float hi) { unsigned r; asm volatile("v_cvt_pk_bf16_f32 %0, %1, %2" : "=v"(r) : "v"(lo), "v"(hi)); return r; }
;     __device__ __forceinline__ void operator()(f32x4 (&acc)[2][2][4][2], const Unit& u, int wr, int wc, int fr, int fq, LAS unsigned char*) const {
;     ...
;             for (int ai = 0; ai < 2; ++ai)
; #pragma unroll
;                 for (int m = 0; m < 4; ++m)
; #pragma unroll
;                     for (int bj = 0; bj < 2; ++bj) { const u32x4 x = xb[ai][m][bj];
;                         f32x4 r0 = (f32x4){__uint_as_float(x.x << 16), __uint_as_float(x.x & 0xffff0000u), __uint_as_float(x.y << 16), __uint_as_float(x.y & 0xffff0000u)};
;                         f32x4 r1 = (f32x4){__uint_as_float(x.z << 16), __uint_as_float(x.z & 0xffff0000u), __uint_as_float(x.w << 16), __uint_as_float(x.w & 0xffff0000u)};
;                         r0 += sc[bj][0] * acc[ai][bj][m][0]; r1 += sc[bj][1] * acc[ai][bj][m][1];
;                         u32x4 w; w.x = cvt_pk_bf16(r0[0], r0[1]); w.y = cvt_pk_bf16(r0[2], r0[3]); w.z = cvt_pk_bf16(r1[0], r1[1]); w.w = cvt_pk_bf16(r1[2], r1[3]);
;                         *(u32x4*)(out + off0 + (size_t)(ai * HALF + m * 16) * D + bj * HALF) = w; }
	v_lshlrev_b32_e32 v84, 16, v166
	v_cvt_pk_bf16_f32 v82, v82, v83
	v_cvt_pk_bf16_f32 v83, v88, v89
	global_store_dwordx4 v[92:93], v[80:83], off offset:256
	v_and_b32_e32 v85, 0xffff0000, v166
	v_lshlrev_b32_e32 v86, 16, v167
	v_lshlrev_b32_e32 v80, 16, v164
	v_and_b32_e32 v81, 0xffff0000, v164
	v_and_b32_e32 v87, 0xffff0000, v167
	v_pk_fma_f32 v[76:77], v[76:77], v[212:213], v[80:81]
	v_lshlrev_b32_e32 v82, 16, v165
	v_and_b32_e32 v83, 0xffff0000, v165
	v_pk_fma_f32 v[80:81], v[74:75], v[210:211], v[86:87]
	v_pk_fma_f32 v[74:75], v[72:73], v[208:209], v[84:85]
	v_cvt_pk_bf16_f32 v72, v76, v77
	v_add_co_u32_e32 v76, vcc, s23, v144
	v_pk_fma_f32 v[78:79], v[78:79], v[214:215], v[82:83]
	s_nop 0
	v_addc_co_u32_e32 v77, vcc, 0, v145, vcc
	v_cvt_pk_bf16_f32 v73, v78, v79
	v_cvt_pk_bf16_f32 v74, v74, v75
	v_cvt_pk_bf16_f32 v75, v80, v81
	global_store_dwordx4 v[76:77], v[72:75], off
	s_waitcnt vmcnt(15)
	v_lshlrev_b32_e32 v78, 16, v162
	v_and_b32_e32 v79, 0xffff0000, v162
	v_lshlrev_b32_e32 v72, 16, v160
	v_and_b32_e32 v73, 0xffff0000, v160
	v_lshlrev_b32_e32 v74, 16, v161
	v_and_b32_e32 v75, 0xffff0000, v161
	v_lshlrev_b32_e32 v80, 16, v163
	v_and_b32_e32 v81, 0xffff0000, v163
	v_pk_fma_f32 v[70:71], v[70:71], v[206:207], v[74:75]
	v_pk_fma_f32 v[68:69], v[68:69], v[204:205], v[72:73]
	v_pk_fma_f32 v[72:73], v[66:67], v[202:203], v[80:81]
	v_pk_fma_f32 v[66:67], v[64:65], v[200:201], v[78:79]
	v_cvt_pk_bf16_f32 v64, v68, v69
	v_cvt_pk_bf16_f32 v65, v70, v71
	s_waitcnt vmcnt(14)
	v_lshlrev_b32_e32 v68, 16, v158
	v_cvt_pk_bf16_f32 v66, v66, v67
	v_cvt_pk_bf16_f32 v67, v72, v73
	global_store_dwordx4 v[76:77], v[64:67], off offset:256
	v_and_b32_e32 v69, 0xffff0000, v158
	v_lshlrev_b32_e32 v70, 16, v159
	v_lshlrev_b32_e32 v64, 16, v156
	v_and_b32_e32 v65, 0xffff0000, v156
	v_and_b32_e32 v71, 0xffff0000, v159
	v_pk_fma_f32 v[60:61], v[60:61], v[212:213], v[64:65]
	v_lshlrev_b32_e32 v66, 16, v157
	v_and_b32_e32 v67, 0xffff0000, v157
	v_pk_fma_f32 v[64:65], v[58:59], v[210:211], v[70:71]
	v_pk_fma_f32 v[58:59], v[56:57], v[208:209], v[68:69]
	v_cvt_pk_bf16_f32 v56, v60, v61
	v_add_co_u32_e32 v60, vcc, s93, v144
	v_pk_fma_f32 v[62:63], v[62:63], v[214:215], v[66:67]
	s_nop 0
	v_addc_co_u32_e32 v61, vcc, 0, v145, vcc
	v_cvt_pk_bf16_f32 v57, v62, v63
	v_cvt_pk_bf16_f32 v58, v58, v59
	v_cvt_pk_bf16_f32 v59, v64, v65
	global_store_dwordx4 v[60:61], v[56:59], off
	s_waitcnt vmcnt(15)
	v_lshlrev_b32_e32 v62, 16, v154
	v_and_b32_e32 v63, 0xffff0000, v154
	v_lshlrev_b32_e32 v56, 16, v152
	v_and_b32_e32 v57, 0xffff0000, v152
	v_lshlrev_b32_e32 v58, 16, v153
	v_and_b32_e32 v59, 0xffff0000, v153
	v_lshlrev_b32_e32 v64, 16, v155
	v_and_b32_e32 v65, 0xffff0000, v155
	v_pk_fma_f32 v[54:55], v[54:55], v[206:207], v[58:59]
	v_pk_fma_f32 v[52:53], v[52:53], v[204:205], v[56:57]
	v_pk_fma_f32 v[56:57], v[50:51], v[202:203], v[64:65]
	v_pk_fma_f32 v[50:51], v[48:49], v[200:201], v[62:63]
	v_cvt_pk_bf16_f32 v48, v52, v53
	v_cvt_pk_bf16_f32 v49, v54, v55
	s_waitcnt vmcnt(14)
	v_lshlrev_b32_e32 v52, 16, v142
	v_cvt_pk_bf16_f32 v50, v50, v51
	v_cvt_pk_bf16_f32 v51, v56, v57
	global_store_dwordx4 v[60:61], v[48:51], off offset:256
	v_and_b32_e32 v53, 0xffff0000, v142
	v_lshlrev_b32_e32 v54, 16, v143
	v_lshlrev_b32_e32 v48, 16, v140
	v_and_b32_e32 v49, 0xffff0000, v140
	v_and_b32_e32 v55, 0xffff0000, v143
	v_pk_fma_f32 v[44:45], v[44:45], v[212:213], v[48:49]
	v_lshlrev_b32_e32 v50, 16, v141
	v_and_b32_e32 v51, 0xffff0000, v141
	v_pk_fma_f32 v[48:49], v[42:43], v[210:211], v[54:55]
	v_pk_fma_f32 v[42:43], v[40:41], v[208:209], v[52:53]
	v_cvt_pk_bf16_f32 v40, v44, v45
	v_add_co_u32_e32 v44, vcc, s33, v144
	v_pk_fma_f32 v[46:47], v[46:47], v[214:215], v[50:51]
	s_nop 0
	v_addc_co_u32_e32 v45, vcc, 0, v145, vcc
	v_cvt_pk_bf16_f32 v41, v46, v47
	v_cvt_pk_bf16_f32 v42, v42, v43
	v_cvt_pk_bf16_f32 v43, v48, v49
	global_store_dwordx4 v[44:45], v[40:43], off
	s_waitcnt vmcnt(15)
; __device__ __forceinline__ unsigned cvt_pk_bf16(float lo, float hi) { unsigned r; asm volatile("v_cvt_pk_bf16_f32 %0, %1, %2" : "=v"(r) : "v"(lo), "v"(hi)); return r; }
; #define PG8_WAIT_V(n) asm volatile("s_waitcnt vmcnt(" #n ")" ::: "memory")
; #define PG8_BAR __builtin_amdgcn_s_barrier()
; template <class Epi>
; __device__ __forceinline__ void gemm_phase(LAS unsigned char* lds, const Gemm g, const StaticOrder& S, const Epi& E) {
;     ...
;         if (!has_next) break;
; #pragma unroll
;         for (int a = 0; a < 2; ++a)
; #pragma unroll
;             for (int b = 0; b < 2; ++b)
; #pragma unroll
;                 for (int m = 0; m < 4; ++m)
; #pragma unroll
;                     for (int n = 0; n < 2; ++n) acc[a][b][m][n] = (f32x4){0.f, 0.f, 0.f, 0.f};
;         cur = nxt; cA = nA; cB = nB; ++ui;
;     }
;     PG8_WAIT_V(0);
;     if (wr == 0) PG8_BAR;
;     PG8_BAR;
;     __device__ __forceinline__ void operator()(f32x4 (&acc)[2][2][4][2], const Unit& u, int wr, int wc, int fr, int fq, LAS unsigned char*) const {
;     ...
;             for (int ai = 0; ai < 2; ++ai)
; #pragma unroll
;                 for (int m = 0; m < 4; ++m)
; #pragma unroll
;                     for (int bj = 0; bj < 2; ++bj) { const u32x4 x = xb[ai][m][bj];
;                         f32x4 r0 = (f32x4){__uint_as_float(x.x << 16), __uint_as_float(x.x & 0xffff0000u), __uint_as_float(x.y << 16), __uint_as_float(x.y & 0xffff0000u)};
;                         f32x4 r1 = (f32x4){__uint_as_float(x.z << 16), __uint_as_float(x.z & 0xffff0000u), __uint_as_float(x.w << 16), __uint_as_float(x.w & 0xffff0000u)};
;                         r0 += sc[bj][0] * acc[ai][bj][m][0]; r1 += sc[bj][1] * acc[ai][bj][m][1];
;                         u32x4 w; w.x = cvt_pk_bf16(r0[0], r0[1]); w.y = cvt_pk_bf16(r0[2], r0[3]); w.z = cvt_pk_bf16(r1[0], r1[1]); w.w = cvt_pk_bf16(r1[2], r1[3]);
;                         *(u32x4*)(out + off0 + (size_t)(ai * HALF + m * 16) * D + bj * HALF) = w; }
	v_lshlrev_b32_e32 v46, 16, v138
	v_and_b32_e32 v47, 0xffff0000, v138
	v_lshlrev_b32_e32 v40, 16, v136
	v_and_b32_e32 v41, 0xffff0000, v136
	v_lshlrev_b32_e32 v42, 16, v137
	v_and_b32_e32 v43, 0xffff0000, v137
	v_lshlrev_b32_e32 v48, 16, v139
	v_and_b32_e32 v49, 0xffff0000, v139
	v_pk_fma_f32 v[38:39], v[38:39], v[206:207], v[42:43]
	v_pk_fma_f32 v[36:37], v[36:37], v[204:205], v[40:41]
	v_pk_fma_f32 v[40:41], v[34:35], v[202:203], v[48:49]
	v_pk_fma_f32 v[34:35], v[32:33], v[200:201], v[46:47]
	v_cvt_pk_bf16_f32 v32, v36, v37
	v_cvt_pk_bf16_f32 v33, v38, v39
	s_waitcnt vmcnt(14)
	v_lshlrev_b32_e32 v36, 16, v134
	v_cvt_pk_bf16_f32 v34, v34, v35
	v_cvt_pk_bf16_f32 v35, v40, v41
	global_store_dwordx4 v[44:45], v[32:35], off offset:256
	v_and_b32_e32 v37, 0xffff0000, v134
	v_lshlrev_b32_e32 v38, 16, v135
	v_lshlrev_b32_e32 v32, 16, v132
	v_and_b32_e32 v33, 0xffff0000, v132
	v_and_b32_e32 v39, 0xffff0000, v135
	v_pk_fma_f32 v[28:29], v[28:29], v[212:213], v[32:33]
	v_lshlrev_b32_e32 v34, 16, v133
	v_and_b32_e32 v35, 0xffff0000, v133
	v_pk_fma_f32 v[32:33], v[26:27], v[210:211], v[38:39]
	v_pk_fma_f32 v[26:27], v[24:25], v[208:209], v[36:37]
	v_cvt_pk_bf16_f32 v24, v28, v29
	v_add_co_u32_e32 v28, vcc, s18, v144
	v_pk_fma_f32 v[30:31], v[30:31], v[214:215], v[34:35]
	s_nop 0
	v_addc_co_u32_e32 v29, vcc, 0, v145, vcc
	v_cvt_pk_bf16_f32 v25, v30, v31
	v_cvt_pk_bf16_f32 v26, v26, v27
	v_cvt_pk_bf16_f32 v27, v32, v33
	global_store_dwordx4 v[28:29], v[24:27], off
	s_waitcnt vmcnt(15)
	v_lshlrev_b32_e32 v30, 16, v130
	v_and_b32_e32 v31, 0xffff0000, v130
	v_lshlrev_b32_e32 v24, 16, v128
	v_and_b32_e32 v25, 0xffff0000, v128
	v_lshlrev_b32_e32 v26, 16, v129
	v_and_b32_e32 v27, 0xffff0000, v129
	v_lshlrev_b32_e32 v32, 16, v131
	v_and_b32_e32 v33, 0xffff0000, v131
	v_pk_fma_f32 v[22:23], v[22:23], v[206:207], v[26:27]
	v_pk_fma_f32 v[20:21], v[20:21], v[204:205], v[24:25]
	v_pk_fma_f32 v[24:25], v[18:19], v[202:203], v[32:33]
	v_pk_fma_f32 v[18:19], v[16:17], v[200:201], v[30:31]
	v_cvt_pk_bf16_f32 v16, v20, v21
	v_cvt_pk_bf16_f32 v17, v22, v23
	s_waitcnt vmcnt(14)
	v_lshlrev_b32_e32 v20, 16, v126
	v_cvt_pk_bf16_f32 v18, v18, v19
	v_cvt_pk_bf16_f32 v19, v24, v25
	global_store_dwordx4 v[28:29], v[16:19], off offset:256
	v_and_b32_e32 v21, 0xffff0000, v126
	v_lshlrev_b32_e32 v22, 16, v127
	v_lshlrev_b32_e32 v16, 16, v124
	v_and_b32_e32 v17, 0xffff0000, v124
	v_and_b32_e32 v23, 0xffff0000, v127
	v_pk_fma_f32 v[12:13], v[12:13], v[212:213], v[16:17]
	v_lshlrev_b32_e32 v18, 16, v125
	v_and_b32_e32 v19, 0xffff0000, v125
	v_pk_fma_f32 v[16:17], v[10:11], v[210:211], v[22:23]
	v_pk_fma_f32 v[10:11], v[8:9], v[208:209], v[20:21]
	v_cvt_pk_bf16_f32 v8, v12, v13
	v_add_co_u32_e32 v12, vcc, s19, v144
	v_pk_fma_f32 v[14:15], v[14:15], v[214:215], v[18:19]
	s_nop 0
	v_addc_co_u32_e32 v13, vcc, 0, v145, vcc
	v_cvt_pk_bf16_f32 v9, v14, v15
	v_cvt_pk_bf16_f32 v10, v10, v11
	v_cvt_pk_bf16_f32 v11, v16, v17
	global_store_dwordx4 v[12:13], v[8:11], off
	s_waitcnt vmcnt(15)
	v_lshlrev_b32_e32 v14, 16, v122
	v_and_b32_e32 v15, 0xffff0000, v122
	v_lshlrev_b32_e32 v8, 16, v120
	v_and_b32_e32 v9, 0xffff0000, v120
	v_lshlrev_b32_e32 v16, 16, v123
	v_and_b32_e32 v17, 0xffff0000, v123
	v_lshlrev_b32_e32 v10, 16, v121
	v_and_b32_e32 v11, 0xffff0000, v121
	v_pk_fma_f32 v[4:5], v[4:5], v[204:205], v[8:9]
	v_pk_fma_f32 v[8:9], v[2:3], v[202:203], v[16:17]
	v_pk_fma_f32 v[2:3], v[0:1], v[200:201], v[14:15]
	s_and_b64 vcc, exec, s[4:5]
	v_pk_fma_f32 v[6:7], v[6:7], v[206:207], v[10:11]
	v_cvt_pk_bf16_f32 v0, v4, v5
	s_nop 0
	v_cvt_pk_bf16_f32 v1, v6, v7
	v_cvt_pk_bf16_f32 v2, v2, v3
	v_cvt_pk_bf16_f32 v3, v8, v9
	global_store_dwordx4 v[12:13], v[0:3], off offset:256
	s_cbranch_vccz .LBB0_849
	s_waitcnt vmcnt(0)
	s_cmpk_gt_u32 s21, 0xff
	v_readlane_b32 s38, v255, 44
	s_cbranch_scc1 .LBB0_864
	s_barrier
